# MERGE and CONVERT bodies hand-written (all loads of a thread in flight); INPROJ register epilogues for q/k/memq head-norm, c_q/c_kv and k_rope tiles (V pairs keep the LDS transpose)
# speedup vs baseline: 1.1250x; 1.0126x over previous
; DI int TID() { int t = (int)__builtin_amdgcn_workitem_id_x(); asm volatile("" : "+v"(t)); return t; }
; DI int BID() { int b = (int)__builtin_amdgcn_workgroup_id_x(); asm volatile("" : "+s"(b)); return b; }
; DI unsigned pk2(float a, float b) { f2_t v = {a, b}; bf2_t r = __builtin_convertvector(v, bf2_t); return __builtin_bit_cast(unsigned, r); }
; DI void phase_convert(const Params& p, const Chunk& ck) {
;   const float* xsrc = chunk_xsrc(p, 0, ck);
;   u16* xb = (u16*)(p.ws + OFF_XB); float* ps = (float*)(p.ws + OFF_PSIN);
;   const int tid = TID(), lane = tid & 63, w = tid >> 6;
;   for (int row = BID() * 4 + w; row < CT; row += gridDim.x * 4) {
;     float ss = 0.f;
; #pragma unroll
;     for (int i = 0; i < 2; ++i) {
;       const int c = (lane + 64 * i) * 8;
;       const f32x4 a = *(const f32x4*)(xsrc + (size_t)row * 1024 + c), b = *(const f32x4*)(xsrc + (size_t)row * 1024 + c + 4);
;       ss += a[0] * a[0] + a[1] * a[1] + a[2] * a[2] + a[3] * a[3] + b[0] * b[0] + b[1] * b[1] + b[2] * b[2] + b[3] * b[3];
;       *(u32x4*)(xb + (size_t)row * 1024 + c) = u32x4{pk2(a[0], a[1]), pk2(a[2], a[3]), pk2(b[0], b[1]), pk2(b[2], b[3])};
;     }
; #pragma unroll
;     for (int o = 32; o >= 1; o >>= 1) ss += __shfl_xor(ss, o);
;     if (lane < 16) ps[(size_t)row * 16 + lane] = (lane == 0) ? ss : 0.f;
;   }
; }
.LBB1_194:
.LBB1_195:
	v_mov_b32_e32 v108, v2
	v_mov_b32_e32 v109, 0
	v_lshlrev_b64 v[16:17], 12, v[108:109]
	v_lshl_add_u64 v[16:17], v[6:7], 0, v[16:17]
	global_load_dwordx4 v[40:43], v[16:17], off
	global_load_dwordx4 v[44:47], v[16:17], off offset:16
	global_load_dwordx4 v[48:51], v[16:17], off offset:2048
	global_load_dwordx4 v[52:55], v[16:17], off offset:2064
	v_add_u32_e32 v110, 0x800, v2
	v_mov_b32_e32 v111, 0
	v_lshlrev_b64 v[16:17], 12, v[110:111]
	v_lshl_add_u64 v[16:17], v[6:7], 0, v[16:17]
	global_load_dwordx4 v[56:59], v[16:17], off
	global_load_dwordx4 v[60:63], v[16:17], off offset:16
	global_load_dwordx4 v[64:67], v[16:17], off offset:2048
	global_load_dwordx4 v[68:71], v[16:17], off offset:2064
	v_add_u32_e32 v112, 0x1000, v2
	v_mov_b32_e32 v113, 0
	v_lshlrev_b64 v[16:17], 12, v[112:113]
	v_lshl_add_u64 v[16:17], v[6:7], 0, v[16:17]
	global_load_dwordx4 v[72:75], v[16:17], off
	global_load_dwordx4 v[76:79], v[16:17], off offset:16
	global_load_dwordx4 v[80:83], v[16:17], off offset:2048
	global_load_dwordx4 v[84:87], v[16:17], off offset:2064
	v_add_u32_e32 v114, 0x1800, v2
	v_mov_b32_e32 v115, 0
	v_lshlrev_b64 v[16:17], 12, v[114:115]
	v_lshl_add_u64 v[16:17], v[6:7], 0, v[16:17]
	global_load_dwordx4 v[88:91], v[16:17], off
	global_load_dwordx4 v[92:95], v[16:17], off offset:16
	global_load_dwordx4 v[96:99], v[16:17], off offset:2048
	global_load_dwordx4 v[100:103], v[16:17], off offset:2064
	s_waitcnt vmcnt(12)
	v_mul_f32_e32 v104, v40, v40
	v_fmac_f32_e32 v104, v41, v41
	v_fmac_f32_e32 v104, v42, v42
	v_fmac_f32_e32 v104, v43, v43
	v_fmac_f32_e32 v104, v44, v44
	v_fmac_f32_e32 v104, v45, v45
	v_fmac_f32_e32 v104, v46, v46
	v_fmac_f32_e32 v104, v47, v47
	v_fmac_f32_e32 v104, v48, v48
	v_fmac_f32_e32 v104, v49, v49
	v_fmac_f32_e32 v104, v50, v50
	v_fmac_f32_e32 v104, v51, v51
	v_fmac_f32_e32 v104, v52, v52
	v_fmac_f32_e32 v104, v53, v53
	v_fmac_f32_e32 v104, v54, v54
	v_fmac_f32_e32 v104, v55, v55
	v_cvt_pk_bf16_f32 v40, v40, v41
	v_cvt_pk_bf16_f32 v41, v42, v43
	v_cvt_pk_bf16_f32 v42, v44, v45
	v_cvt_pk_bf16_f32 v43, v46, v47
	v_cvt_pk_bf16_f32 v44, v48, v49
	v_cvt_pk_bf16_f32 v45, v50, v51
	v_cvt_pk_bf16_f32 v46, v52, v53
	v_cvt_pk_bf16_f32 v47, v54, v55
	v_lshlrev_b64 v[16:17], 6, v[108:109]
	v_lshl_add_u64 v[16:17], v[8:9], 0, v[16:17]
	global_store_dwordx4 v[16:17], v[40:43], off
	v_lshl_add_u64 v[16:17], v[16:17], 0, s[16:17]
	global_store_dwordx4 v[16:17], v[44:47], off
	s_waitcnt vmcnt(8)
	v_mul_f32_e32 v105, v56, v56
	v_fmac_f32_e32 v105, v57, v57
	v_fmac_f32_e32 v105, v58, v58
	v_fmac_f32_e32 v105, v59, v59
	v_fmac_f32_e32 v105, v60, v60
	v_fmac_f32_e32 v105, v61, v61
	v_fmac_f32_e32 v105, v62, v62
	v_fmac_f32_e32 v105, v63, v63
	v_fmac_f32_e32 v105, v64, v64
	v_fmac_f32_e32 v105, v65, v65
	v_fmac_f32_e32 v105, v66, v66
	v_fmac_f32_e32 v105, v67, v67
	v_fmac_f32_e32 v105, v68, v68
	v_fmac_f32_e32 v105, v69, v69
	v_fmac_f32_e32 v105, v70, v70
	v_fmac_f32_e32 v105, v71, v71
	v_cvt_pk_bf16_f32 v56, v56, v57
	v_cvt_pk_bf16_f32 v57, v58, v59
	v_cvt_pk_bf16_f32 v58, v60, v61
	v_cvt_pk_bf16_f32 v59, v62, v63
	v_cvt_pk_bf16_f32 v60, v64, v65
	v_cvt_pk_bf16_f32 v61, v66, v67
	v_cvt_pk_bf16_f32 v62, v68, v69
	v_cvt_pk_bf16_f32 v63, v70, v71
	v_lshlrev_b64 v[16:17], 6, v[110:111]
	v_lshl_add_u64 v[16:17], v[8:9], 0, v[16:17]
	global_store_dwordx4 v[16:17], v[56:59], off
	v_lshl_add_u64 v[16:17], v[16:17], 0, s[16:17]
	global_store_dwordx4 v[16:17], v[60:63], off
	s_waitcnt vmcnt(4)
	v_mul_f32_e32 v106, v72, v72
	v_fmac_f32_e32 v106, v73, v73
	v_fmac_f32_e32 v106, v74, v74
	v_fmac_f32_e32 v106, v75, v75
	v_fmac_f32_e32 v106, v76, v76
	v_fmac_f32_e32 v106, v77, v77
	v_fmac_f32_e32 v106, v78, v78
	v_fmac_f32_e32 v106, v79, v79
	v_fmac_f32_e32 v106, v80, v80
	v_fmac_f32_e32 v106, v81, v81
	v_fmac_f32_e32 v106, v82, v82
	v_fmac_f32_e32 v106, v83, v83
	v_fmac_f32_e32 v106, v84, v84
	v_fmac_f32_e32 v106, v85, v85
	v_fmac_f32_e32 v106, v86, v86
	v_fmac_f32_e32 v106, v87, v87
	v_cvt_pk_bf16_f32 v72, v72, v73
	v_cvt_pk_bf16_f32 v73, v74, v75
	v_cvt_pk_bf16_f32 v74, v76, v77
	v_cvt_pk_bf16_f32 v75, v78, v79
	v_cvt_pk_bf16_f32 v76, v80, v81
	v_cvt_pk_bf16_f32 v77, v82, v83
	v_cvt_pk_bf16_f32 v78, v84, v85
	v_cvt_pk_bf16_f32 v79, v86, v87
	v_lshlrev_b64 v[16:17], 6, v[112:113]
	v_lshl_add_u64 v[16:17], v[8:9], 0, v[16:17]
	global_store_dwordx4 v[16:17], v[72:75], off
	v_lshl_add_u64 v[16:17], v[16:17], 0, s[16:17]
	global_store_dwordx4 v[16:17], v[76:79], off
	s_waitcnt vmcnt(0)
; DI int BID() { int b = (int)__builtin_amdgcn_workgroup_id_x(); asm volatile("" : "+s"(b)); return b; }
; DI unsigned pk2(float a, float b) { f2_t v = {a, b}; bf2_t r = __builtin_convertvector(v, bf2_t); return __builtin_bit_cast(unsigned, r); }
; DI void phase_convert(const Params& p, const Chunk& ck) {
;     ...
;   for (int row = BID() * 4 + w; row < CT; row += gridDim.x * 4) {
;     float ss = 0.f;
; #pragma unroll
;     for (int i = 0; i < 2; ++i) {
;       const int c = (lane + 64 * i) * 8;
;       const f32x4 a = *(const f32x4*)(xsrc + (size_t)row * 1024 + c), b = *(const f32x4*)(xsrc + (size_t)row * 1024 + c + 4);
;       ss += a[0] * a[0] + a[1] * a[1] + a[2] * a[2] + a[3] * a[3] + b[0] * b[0] + b[1] * b[1] + b[2] * b[2] + b[3] * b[3];
;       *(u32x4*)(xb + (size_t)row * 1024 + c) = u32x4{pk2(a[0], a[1]), pk2(a[2], a[3]), pk2(b[0], b[1]), pk2(b[2], b[3])};
;     }
; #pragma unroll
;     for (int o = 32; o >= 1; o >>= 1) ss += __shfl_xor(ss, o);
;     if (lane < 16) ps[(size_t)row * 16 + lane] = (lane == 0) ? ss : 0.f;
;   }
; }
	v_mul_f32_e32 v107, v88, v88
	v_fmac_f32_e32 v107, v89, v89
	v_fmac_f32_e32 v107, v90, v90
	v_fmac_f32_e32 v107, v91, v91
	v_fmac_f32_e32 v107, v92, v92
	v_fmac_f32_e32 v107, v93, v93
	v_fmac_f32_e32 v107, v94, v94
	v_fmac_f32_e32 v107, v95, v95
	v_fmac_f32_e32 v107, v96, v96
	v_fmac_f32_e32 v107, v97, v97
	v_fmac_f32_e32 v107, v98, v98
	v_fmac_f32_e32 v107, v99, v99
	v_fmac_f32_e32 v107, v100, v100
	v_fmac_f32_e32 v107, v101, v101
	v_fmac_f32_e32 v107, v102, v102
	v_fmac_f32_e32 v107, v103, v103
	v_cvt_pk_bf16_f32 v88, v88, v89
	v_cvt_pk_bf16_f32 v89, v90, v91
	v_cvt_pk_bf16_f32 v90, v92, v93
	v_cvt_pk_bf16_f32 v91, v94, v95
	v_cvt_pk_bf16_f32 v92, v96, v97
	v_cvt_pk_bf16_f32 v93, v98, v99
	v_cvt_pk_bf16_f32 v94, v100, v101
	v_cvt_pk_bf16_f32 v95, v102, v103
	v_lshlrev_b64 v[16:17], 6, v[114:115]
	v_lshl_add_u64 v[16:17], v[8:9], 0, v[16:17]
	global_store_dwordx4 v[16:17], v[88:91], off
	v_lshl_add_u64 v[16:17], v[16:17], 0, s[16:17]
	global_store_dwordx4 v[16:17], v[92:95], off
	v_add_f32_dpp v104, v104, v104 quad_perm:[1,0,3,2] row_mask:0xf bank_mask:0xf
	v_add_f32_dpp v105, v105, v105 quad_perm:[1,0,3,2] row_mask:0xf bank_mask:0xf
	v_add_f32_dpp v106, v106, v106 quad_perm:[1,0,3,2] row_mask:0xf bank_mask:0xf
	v_add_f32_dpp v107, v107, v107 quad_perm:[1,0,3,2] row_mask:0xf bank_mask:0xf
	v_add_f32_dpp v104, v104, v104 quad_perm:[2,3,0,1] row_mask:0xf bank_mask:0xf
	v_add_f32_dpp v105, v105, v105 quad_perm:[2,3,0,1] row_mask:0xf bank_mask:0xf
	v_add_f32_dpp v106, v106, v106 quad_perm:[2,3,0,1] row_mask:0xf bank_mask:0xf
	v_add_f32_dpp v107, v107, v107 quad_perm:[2,3,0,1] row_mask:0xf bank_mask:0xf
	v_add_f32_dpp v104, v104, v104 row_half_mirror row_mask:0xf bank_mask:0xf
	v_add_f32_dpp v105, v105, v105 row_half_mirror row_mask:0xf bank_mask:0xf
	v_add_f32_dpp v106, v106, v106 row_half_mirror row_mask:0xf bank_mask:0xf
	v_add_f32_dpp v107, v107, v107 row_half_mirror row_mask:0xf bank_mask:0xf
	v_add_f32_dpp v104, v104, v104 row_mirror row_mask:0xf bank_mask:0xf
	v_add_f32_dpp v105, v105, v105 row_mirror row_mask:0xf bank_mask:0xf
	v_add_f32_dpp v106, v106, v106 row_mirror row_mask:0xf bank_mask:0xf
	v_add_f32_dpp v107, v107, v107 row_mirror row_mask:0xf bank_mask:0xf
	ds_swizzle_b32 v116, v104 offset:0x401f
	ds_swizzle_b32 v117, v105 offset:0x401f
	ds_swizzle_b32 v118, v106 offset:0x401f
	ds_swizzle_b32 v119, v107 offset:0x401f
	s_waitcnt lgkmcnt(0)
	v_add_f32_e32 v104, v104, v116
	v_add_f32_e32 v105, v105, v117
	v_add_f32_e32 v106, v106, v118
	v_add_f32_e32 v107, v107, v119
	v_mov_b32_e32 v116, v104
	v_mov_b32_e32 v117, v105
	v_mov_b32_e32 v118, v106
	v_mov_b32_e32 v119, v107
	s_nop 1
	v_permlane32_swap_b32_e32 v104, v116
	v_permlane32_swap_b32_e32 v105, v117
	v_permlane32_swap_b32_e32 v106, v118
	v_permlane32_swap_b32_e32 v107, v119
	s_nop 1
	v_add_f32_e32 v104, v104, v116
	v_add_f32_e32 v105, v105, v117
	v_add_f32_e32 v106, v106, v118
	v_add_f32_e32 v107, v107, v119
	v_cndmask_b32_e64 v104, 0, v104, s[36:37]
	v_cndmask_b32_e64 v105, 0, v105, s[36:37]
	v_cndmask_b32_e64 v106, 0, v106, s[36:37]
	v_cndmask_b32_e64 v107, 0, v107, s[36:37]
	s_and_saveexec_b64 s[26:27], vcc
	v_lshlrev_b64 v[16:17], 6, v[108:109]
	v_lshl_add_u64 v[16:17], v[4:5], 0, v[16:17]
	global_store_dword v[16:17], v104, off
	v_lshlrev_b64 v[16:17], 6, v[110:111]
	v_lshl_add_u64 v[16:17], v[4:5], 0, v[16:17]
	global_store_dword v[16:17], v105, off
	v_lshlrev_b64 v[16:17], 6, v[112:113]
	v_lshl_add_u64 v[16:17], v[4:5], 0, v[16:17]
	global_store_dword v[16:17], v106, off
	v_lshlrev_b64 v[16:17], 6, v[114:115]
	v_lshl_add_u64 v[16:17], v[4:5], 0, v[16:17]
	global_store_dword v[16:17], v107, off
	s_or_b64 exec, exec, s[26:27]
	v_add_u32_e32 v108, 0x2000, v2
	v_mov_b32_e32 v109, 0
	v_lshlrev_b64 v[16:17], 12, v[108:109]
	v_lshl_add_u64 v[16:17], v[6:7], 0, v[16:17]
	global_load_dwordx4 v[40:43], v[16:17], off
	global_load_dwordx4 v[44:47], v[16:17], off offset:16
	global_load_dwordx4 v[48:51], v[16:17], off offset:2048
	global_load_dwordx4 v[52:55], v[16:17], off offset:2064
	v_add_u32_e32 v110, 0x2800, v2
	v_mov_b32_e32 v111, 0
	v_lshlrev_b64 v[16:17], 12, v[110:111]
	v_lshl_add_u64 v[16:17], v[6:7], 0, v[16:17]
	global_load_dwordx4 v[56:59], v[16:17], off
	global_load_dwordx4 v[60:63], v[16:17], off offset:16
	global_load_dwordx4 v[64:67], v[16:17], off offset:2048
	global_load_dwordx4 v[68:71], v[16:17], off offset:2064
	v_add_u32_e32 v112, 0x3000, v2
	v_mov_b32_e32 v113, 0
	v_lshlrev_b64 v[16:17], 12, v[112:113]
	v_lshl_add_u64 v[16:17], v[6:7], 0, v[16:17]
	global_load_dwordx4 v[72:75], v[16:17], off
	global_load_dwordx4 v[76:79], v[16:17], off offset:16
	global_load_dwordx4 v[80:83], v[16:17], off offset:2048
	global_load_dwordx4 v[84:87], v[16:17], off offset:2064
	v_add_u32_e32 v114, 0x3800, v2
	v_mov_b32_e32 v115, 0
	v_lshlrev_b64 v[16:17], 12, v[114:115]
	v_lshl_add_u64 v[16:17], v[6:7], 0, v[16:17]
	global_load_dwordx4 v[88:91], v[16:17], off
	global_load_dwordx4 v[92:95], v[16:17], off offset:16
	global_load_dwordx4 v[96:99], v[16:17], off offset:2048
	global_load_dwordx4 v[100:103], v[16:17], off offset:2064
	s_waitcnt vmcnt(12)
	v_mul_f32_e32 v104, v40, v40
	v_fmac_f32_e32 v104, v41, v41
	v_fmac_f32_e32 v104, v42, v42
	v_fmac_f32_e32 v104, v43, v43
	v_fmac_f32_e32 v104, v44, v44
	v_fmac_f32_e32 v104, v45, v45
	v_fmac_f32_e32 v104, v46, v46
	v_fmac_f32_e32 v104, v47, v47
	v_fmac_f32_e32 v104, v48, v48
	v_fmac_f32_e32 v104, v49, v49
	v_fmac_f32_e32 v104, v50, v50
	v_fmac_f32_e32 v104, v51, v51
	v_fmac_f32_e32 v104, v52, v52
	v_fmac_f32_e32 v104, v53, v53
	v_fmac_f32_e32 v104, v54, v54
	v_fmac_f32_e32 v104, v55, v55
	v_cvt_pk_bf16_f32 v40, v40, v41
	v_cvt_pk_bf16_f32 v41, v42, v43
	v_cvt_pk_bf16_f32 v42, v44, v45
	v_cvt_pk_bf16_f32 v43, v46, v47
	v_cvt_pk_bf16_f32 v44, v48, v49
	v_cvt_pk_bf16_f32 v45, v50, v51
	v_cvt_pk_bf16_f32 v46, v52, v53
	v_cvt_pk_bf16_f32 v47, v54, v55
	v_lshlrev_b64 v[16:17], 6, v[108:109]
	v_lshl_add_u64 v[16:17], v[8:9], 0, v[16:17]
	global_store_dwordx4 v[16:17], v[40:43], off
	v_lshl_add_u64 v[16:17], v[16:17], 0, s[16:17]
	global_store_dwordx4 v[16:17], v[44:47], off
	s_waitcnt vmcnt(8)
; DI int BID() { int b = (int)__builtin_amdgcn_workgroup_id_x(); asm volatile("" : "+s"(b)); return b; }
; DI unsigned pk2(float a, float b) { f2_t v = {a, b}; bf2_t r = __builtin_convertvector(v, bf2_t); return __builtin_bit_cast(unsigned, r); }
; DI void phase_convert(const Params& p, const Chunk& ck) {
;     ...
;   for (int row = BID() * 4 + w; row < CT; row += gridDim.x * 4) {
;     float ss = 0.f;
; #pragma unroll
;     for (int i = 0; i < 2; ++i) {
;       const int c = (lane + 64 * i) * 8;
;       const f32x4 a = *(const f32x4*)(xsrc + (size_t)row * 1024 + c), b = *(const f32x4*)(xsrc + (size_t)row * 1024 + c + 4);
;       ss += a[0] * a[0] + a[1] * a[1] + a[2] * a[2] + a[3] * a[3] + b[0] * b[0] + b[1] * b[1] + b[2] * b[2] + b[3] * b[3];
;       *(u32x4*)(xb + (size_t)row * 1024 + c) = u32x4{pk2(a[0], a[1]), pk2(a[2], a[3]), pk2(b[0], b[1]), pk2(b[2], b[3])};
;     }
; #pragma unroll
;     for (int o = 32; o >= 1; o >>= 1) ss += __shfl_xor(ss, o);
;     if (lane < 16) ps[(size_t)row * 16 + lane] = (lane == 0) ? ss : 0.f;
;   }
; }
	v_mul_f32_e32 v105, v56, v56
	v_fmac_f32_e32 v105, v57, v57
	v_fmac_f32_e32 v105, v58, v58
	v_fmac_f32_e32 v105, v59, v59
	v_fmac_f32_e32 v105, v60, v60
	v_fmac_f32_e32 v105, v61, v61
	v_fmac_f32_e32 v105, v62, v62
	v_fmac_f32_e32 v105, v63, v63
	v_fmac_f32_e32 v105, v64, v64
	v_fmac_f32_e32 v105, v65, v65
	v_fmac_f32_e32 v105, v66, v66
	v_fmac_f32_e32 v105, v67, v67
	v_fmac_f32_e32 v105, v68, v68
	v_fmac_f32_e32 v105, v69, v69
	v_fmac_f32_e32 v105, v70, v70
	v_fmac_f32_e32 v105, v71, v71
	v_cvt_pk_bf16_f32 v56, v56, v57
	v_cvt_pk_bf16_f32 v57, v58, v59
	v_cvt_pk_bf16_f32 v58, v60, v61
	v_cvt_pk_bf16_f32 v59, v62, v63
	v_cvt_pk_bf16_f32 v60, v64, v65
	v_cvt_pk_bf16_f32 v61, v66, v67
	v_cvt_pk_bf16_f32 v62, v68, v69
	v_cvt_pk_bf16_f32 v63, v70, v71
	v_lshlrev_b64 v[16:17], 6, v[110:111]
	v_lshl_add_u64 v[16:17], v[8:9], 0, v[16:17]
	global_store_dwordx4 v[16:17], v[56:59], off
	v_lshl_add_u64 v[16:17], v[16:17], 0, s[16:17]
	global_store_dwordx4 v[16:17], v[60:63], off
	s_waitcnt vmcnt(4)
	v_mul_f32_e32 v106, v72, v72
	v_fmac_f32_e32 v106, v73, v73
	v_fmac_f32_e32 v106, v74, v74
	v_fmac_f32_e32 v106, v75, v75
	v_fmac_f32_e32 v106, v76, v76
	v_fmac_f32_e32 v106, v77, v77
	v_fmac_f32_e32 v106, v78, v78
	v_fmac_f32_e32 v106, v79, v79
	v_fmac_f32_e32 v106, v80, v80
	v_fmac_f32_e32 v106, v81, v81
	v_fmac_f32_e32 v106, v82, v82
	v_fmac_f32_e32 v106, v83, v83
	v_fmac_f32_e32 v106, v84, v84
	v_fmac_f32_e32 v106, v85, v85
	v_fmac_f32_e32 v106, v86, v86
	v_fmac_f32_e32 v106, v87, v87
	v_cvt_pk_bf16_f32 v72, v72, v73
	v_cvt_pk_bf16_f32 v73, v74, v75
	v_cvt_pk_bf16_f32 v74, v76, v77
	v_cvt_pk_bf16_f32 v75, v78, v79
	v_cvt_pk_bf16_f32 v76, v80, v81
	v_cvt_pk_bf16_f32 v77, v82, v83
	v_cvt_pk_bf16_f32 v78, v84, v85
	v_cvt_pk_bf16_f32 v79, v86, v87
	v_lshlrev_b64 v[16:17], 6, v[112:113]
	v_lshl_add_u64 v[16:17], v[8:9], 0, v[16:17]
	global_store_dwordx4 v[16:17], v[72:75], off
	v_lshl_add_u64 v[16:17], v[16:17], 0, s[16:17]
	global_store_dwordx4 v[16:17], v[76:79], off
	s_waitcnt vmcnt(0)
	v_mul_f32_e32 v107, v88, v88
	v_fmac_f32_e32 v107, v89, v89
	v_fmac_f32_e32 v107, v90, v90
	v_fmac_f32_e32 v107, v91, v91
	v_fmac_f32_e32 v107, v92, v92
	v_fmac_f32_e32 v107, v93, v93
	v_fmac_f32_e32 v107, v94, v94
	v_fmac_f32_e32 v107, v95, v95
	v_fmac_f32_e32 v107, v96, v96
	v_fmac_f32_e32 v107, v97, v97
	v_fmac_f32_e32 v107, v98, v98
	v_fmac_f32_e32 v107, v99, v99
	v_fmac_f32_e32 v107, v100, v100
	v_fmac_f32_e32 v107, v101, v101
	v_fmac_f32_e32 v107, v102, v102
	v_fmac_f32_e32 v107, v103, v103
	v_cvt_pk_bf16_f32 v88, v88, v89
	v_cvt_pk_bf16_f32 v89, v90, v91
	v_cvt_pk_bf16_f32 v90, v92, v93
	v_cvt_pk_bf16_f32 v91, v94, v95
	v_cvt_pk_bf16_f32 v92, v96, v97
	v_cvt_pk_bf16_f32 v93, v98, v99
	v_cvt_pk_bf16_f32 v94, v100, v101
	v_cvt_pk_bf16_f32 v95, v102, v103
	v_lshlrev_b64 v[16:17], 6, v[114:115]
	v_lshl_add_u64 v[16:17], v[8:9], 0, v[16:17]
	global_store_dwordx4 v[16:17], v[88:91], off
	v_lshl_add_u64 v[16:17], v[16:17], 0, s[16:17]
	global_store_dwordx4 v[16:17], v[92:95], off
	v_add_f32_dpp v104, v104, v104 quad_perm:[1,0,3,2] row_mask:0xf bank_mask:0xf
	v_add_f32_dpp v105, v105, v105 quad_perm:[1,0,3,2] row_mask:0xf bank_mask:0xf
	v_add_f32_dpp v106, v106, v106 quad_perm:[1,0,3,2] row_mask:0xf bank_mask:0xf
	v_add_f32_dpp v107, v107, v107 quad_perm:[1,0,3,2] row_mask:0xf bank_mask:0xf
	v_add_f32_dpp v104, v104, v104 quad_perm:[2,3,0,1] row_mask:0xf bank_mask:0xf
	v_add_f32_dpp v105, v105, v105 quad_perm:[2,3,0,1] row_mask:0xf bank_mask:0xf
	v_add_f32_dpp v106, v106, v106 quad_perm:[2,3,0,1] row_mask:0xf bank_mask:0xf
	v_add_f32_dpp v107, v107, v107 quad_perm:[2,3,0,1] row_mask:0xf bank_mask:0xf
	v_add_f32_dpp v104, v104, v104 row_half_mirror row_mask:0xf bank_mask:0xf
	v_add_f32_dpp v105, v105, v105 row_half_mirror row_mask:0xf bank_mask:0xf
	v_add_f32_dpp v106, v106, v106 row_half_mirror row_mask:0xf bank_mask:0xf
	v_add_f32_dpp v107, v107, v107 row_half_mirror row_mask:0xf bank_mask:0xf
	v_add_f32_dpp v104, v104, v104 row_mirror row_mask:0xf bank_mask:0xf
	v_add_f32_dpp v105, v105, v105 row_mirror row_mask:0xf bank_mask:0xf
	v_add_f32_dpp v106, v106, v106 row_mirror row_mask:0xf bank_mask:0xf
	v_add_f32_dpp v107, v107, v107 row_mirror row_mask:0xf bank_mask:0xf
	ds_swizzle_b32 v116, v104 offset:0x401f
	ds_swizzle_b32 v117, v105 offset:0x401f
	ds_swizzle_b32 v118, v106 offset:0x401f
	ds_swizzle_b32 v119, v107 offset:0x401f
	s_waitcnt lgkmcnt(0)
	v_add_f32_e32 v104, v104, v116
	v_add_f32_e32 v105, v105, v117
	v_add_f32_e32 v106, v106, v118
	v_add_f32_e32 v107, v107, v119
	v_mov_b32_e32 v116, v104
	v_mov_b32_e32 v117, v105
	v_mov_b32_e32 v118, v106
	v_mov_b32_e32 v119, v107
	s_nop 1
	v_permlane32_swap_b32_e32 v104, v116
	v_permlane32_swap_b32_e32 v105, v117
	v_permlane32_swap_b32_e32 v106, v118
	v_permlane32_swap_b32_e32 v107, v119
	s_nop 1
	v_add_f32_e32 v104, v104, v116
	v_add_f32_e32 v105, v105, v117
	v_add_f32_e32 v106, v106, v118
	v_add_f32_e32 v107, v107, v119
	v_cndmask_b32_e64 v104, 0, v104, s[36:37]
	v_cndmask_b32_e64 v105, 0, v105, s[36:37]
	v_cndmask_b32_e64 v106, 0, v106, s[36:37]
	v_cndmask_b32_e64 v107, 0, v107, s[36:37]
	s_and_saveexec_b64 s[26:27], vcc
	v_lshlrev_b64 v[16:17], 6, v[108:109]
	v_lshl_add_u64 v[16:17], v[4:5], 0, v[16:17]
	global_store_dword v[16:17], v104, off
	v_lshlrev_b64 v[16:17], 6, v[110:111]
	v_lshl_add_u64 v[16:17], v[4:5], 0, v[16:17]
	global_store_dword v[16:17], v105, off
	v_lshlrev_b64 v[16:17], 6, v[112:113]
	v_lshl_add_u64 v[16:17], v[4:5], 0, v[16:17]
	global_store_dword v[16:17], v106, off
	v_lshlrev_b64 v[16:17], 6, v[114:115]
	v_lshl_add_u64 v[16:17], v[4:5], 0, v[16:17]
	global_store_dword v[16:17], v107, off
	s_or_b64 exec, exec, s[26:27]

; DI int TID() { int t = (int)__builtin_amdgcn_workitem_id_x(); asm volatile("" : "+v"(t)); return t; }
; DI int BID() { int b = (int)__builtin_amdgcn_workgroup_id_x(); asm volatile("" : "+s"(b)); return b; }
; DI void st8(u16* dst, const float (&v)[8]) { *(u32x4*)dst = pack8(v); }
; DI void phase_merge(const Params& p) {
;   const int gsz = gridDim.x * 256;
;   const u16* AO = (const u16*)(p.ws + OFF_AO); const float* LSE = (const float*)(p.ws + OFF_LSE); u16* BR0 = (u16*)(p.ws + OFF_BR);
;   for (int i = BID() * 256 + TID(); i < CT * 64; i += gsz) {
;     const int lt = i >> 6, c8 = i & 63, h = c8 >> 4;
;     const float l0 = LSE[(size_t)(0 * CT + lt) * 4 + h], l1 = LSE[(size_t)(1 * CT + lt) * 4 + h], l2 = LSE[(size_t)(2 * CT + lt) * 4 + h];
;     const float mx = fmaxf(l0, fmaxf(l1, l2));
;     float w0 = __expf(l0 - mx), w1 = __expf(l1 - mx), w2 = __expf(l2 - mx); const float inv = 1.f / (w0 + w1 + w2); w0 *= inv; w1 *= inv; w2 *= inv;
;     float a[8], b[8], c[8], o[8];
;     unpack8(*(const u32x4*)(AO + (size_t)(0 * CT + lt) * 512 + c8 * 8), a);
;     unpack8(*(const u32x4*)(AO + (size_t)(1 * CT + lt) * 512 + c8 * 8), b);
;     unpack8(*(const u32x4*)(AO + (size_t)(2 * CT + lt) * 512 + c8 * 8), c);
; #pragma unroll
;     for (int j = 0; j < 8; ++j) o[j] = w0 * a[j] + w1 * b[j] + w2 * c[j];
;     st8(BR0 + (size_t)lt * 512 + c8 * 8, o);
;   }
.LBB1_271:
	v_lshrrev_b32_e32 v11, 6, v8
	v_and_b32_e32 v12, 63, v172
	v_lshrrev_b32_e32 v9, 4, v12
	v_lshlrev_b32_e32 v9, 2, v9
	v_lshl_add_u32 v9, v11, 4, v9
	v_lshlrev_b32_e32 v10, 4, v12
	v_lshl_add_u32 v10, v11, 10, v10
	s_add_u32 s16, s18, 0x19080000
	s_addc_u32 s17, s19, 0
	s_add_u32 s22, s18, 0x16080000
	s_addc_u32 s23, s19, 0
	s_add_u32 s26, s18, 0x19140000
	s_addc_u32 s27, s19, 0
	global_load_dword v16, v9, s[16:17]
	v_add_u32_e32 v12, 0x40000, v9
	global_load_dword v17, v12, s[16:17]
	v_add_u32_e32 v11, 0x80000, v9
	global_load_dword v18, v11, s[16:17]
	v_add_u32_e32 v12, 0x8000, v9
	global_load_dword v19, v12, s[16:17]
	v_add_u32_e32 v11, 0x48000, v9
	global_load_dword v20, v11, s[16:17]
	v_add_u32_e32 v12, 0x88000, v9
	global_load_dword v21, v12, s[16:17]
	v_add_u32_e32 v11, 0x10000, v9
	global_load_dword v22, v11, s[16:17]
	v_add_u32_e32 v12, 0x50000, v9
	global_load_dword v23, v12, s[16:17]
	v_add_u32_e32 v11, 0x90000, v9
	global_load_dword v24, v11, s[16:17]
	v_add_u32_e32 v12, 0x18000, v9
	global_load_dword v25, v12, s[16:17]
	v_add_u32_e32 v11, 0x58000, v9
	global_load_dword v26, v11, s[16:17]
	v_add_u32_e32 v12, 0x98000, v9
	global_load_dword v27, v12, s[16:17]
	global_load_dwordx4 v[40:43], v10, s[22:23]
	v_add_u32_e32 v12, 0x1000000, v10
	global_load_dwordx4 v[44:47], v12, s[22:23]
	v_add_u32_e32 v11, 0x2000000, v10
	global_load_dwordx4 v[48:51], v11, s[22:23]
	v_add_u32_e32 v12, 0x200000, v10
	global_load_dwordx4 v[52:55], v12, s[22:23]
	v_add_u32_e32 v11, 0x1200000, v10
	global_load_dwordx4 v[56:59], v11, s[22:23]
	v_add_u32_e32 v12, 0x2200000, v10
	global_load_dwordx4 v[60:63], v12, s[22:23]
	v_add_u32_e32 v11, 0x400000, v10
	global_load_dwordx4 v[64:67], v11, s[22:23]
	v_add_u32_e32 v12, 0x1400000, v10
	global_load_dwordx4 v[68:71], v12, s[22:23]
	v_add_u32_e32 v11, 0x2400000, v10
	global_load_dwordx4 v[72:75], v11, s[22:23]
	v_add_u32_e32 v12, 0x600000, v10
	global_load_dwordx4 v[76:79], v12, s[22:23]
	v_add_u32_e32 v11, 0x1600000, v10
	global_load_dwordx4 v[80:83], v11, s[22:23]
	v_add_u32_e32 v12, 0x2600000, v10
	global_load_dwordx4 v[84:87], v12, s[22:23]
	s_waitcnt vmcnt(12)
	v_max3_f32 v31, v16, v17, v18
	v_sub_f32_e32 v28, v16, v31
	v_sub_f32_e32 v29, v17, v31
	v_sub_f32_e32 v30, v18, v31
	v_mul_f32_e32 v28, 0x3fb8aa3b, v28
	v_mul_f32_e32 v29, 0x3fb8aa3b, v29
	v_mul_f32_e32 v30, 0x3fb8aa3b, v30
	v_exp_f32_e32 v28, v28
	v_exp_f32_e32 v29, v29
	v_exp_f32_e32 v30, v30
	s_nop 0
	v_add_f32_e32 v32, v28, v29
	v_add_f32_e32 v32, v30, v32
	v_rcp_f32_e32 v32, v32
	s_nop 0
	v_mul_f32_e32 v28, v28, v32
	v_mul_f32_e32 v29, v29, v32
	v_mul_f32_e32 v30, v30, v32
	s_waitcnt vmcnt(9)
	v_lshlrev_b32_e32 v88, 16, v40
	v_and_b32_e32 v89, 0xffff0000, v40
	v_lshlrev_b32_e32 v90, 16, v44
	v_and_b32_e32 v91, 0xffff0000, v44
	v_lshlrev_b32_e32 v92, 16, v48
	v_and_b32_e32 v93, 0xffff0000, v48
	v_mul_f32_e32 v88, v28, v88
	v_mul_f32_e32 v89, v28, v89
	v_fmac_f32_e32 v88, v29, v90
	v_fmac_f32_e32 v89, v29, v91
	v_fmac_f32_e32 v88, v30, v92
	v_fmac_f32_e32 v89, v30, v93
	v_cvt_pk_bf16_f32 v40, v88, v89
	v_lshlrev_b32_e32 v88, 16, v41
	v_and_b32_e32 v89, 0xffff0000, v41
	v_lshlrev_b32_e32 v90, 16, v45
	v_and_b32_e32 v91, 0xffff0000, v45
	v_lshlrev_b32_e32 v92, 16, v49
	v_and_b32_e32 v93, 0xffff0000, v49
	v_mul_f32_e32 v88, v28, v88
	v_mul_f32_e32 v89, v28, v89
	v_fmac_f32_e32 v88, v29, v90
	v_fmac_f32_e32 v89, v29, v91
	v_fmac_f32_e32 v88, v30, v92
	v_fmac_f32_e32 v89, v30, v93
	v_cvt_pk_bf16_f32 v41, v88, v89
	v_lshlrev_b32_e32 v88, 16, v42
	v_and_b32_e32 v89, 0xffff0000, v42
	v_lshlrev_b32_e32 v90, 16, v46
	v_and_b32_e32 v91, 0xffff0000, v46
	v_lshlrev_b32_e32 v92, 16, v50
	v_and_b32_e32 v93, 0xffff0000, v50
	v_mul_f32_e32 v88, v28, v88
	v_mul_f32_e32 v89, v28, v89
	v_fmac_f32_e32 v88, v29, v90
	v_fmac_f32_e32 v89, v29, v91
	v_fmac_f32_e32 v88, v30, v92
	v_fmac_f32_e32 v89, v30, v93
	v_cvt_pk_bf16_f32 v42, v88, v89
	v_lshlrev_b32_e32 v88, 16, v43
	v_and_b32_e32 v89, 0xffff0000, v43
	v_lshlrev_b32_e32 v90, 16, v47
	v_and_b32_e32 v91, 0xffff0000, v47
	v_lshlrev_b32_e32 v92, 16, v51
	v_and_b32_e32 v93, 0xffff0000, v51
	v_mul_f32_e32 v88, v28, v88
	v_mul_f32_e32 v89, v28, v89
	v_fmac_f32_e32 v88, v29, v90
	v_fmac_f32_e32 v89, v29, v91
	v_fmac_f32_e32 v88, v30, v92
	v_fmac_f32_e32 v89, v30, v93
	v_cvt_pk_bf16_f32 v43, v88, v89
	global_store_dwordx4 v10, v[40:43], s[26:27]
	v_max3_f32 v31, v19, v20, v21
	v_sub_f32_e32 v28, v19, v31
	v_sub_f32_e32 v29, v20, v31
	v_sub_f32_e32 v30, v21, v31
	v_mul_f32_e32 v28, 0x3fb8aa3b, v28
	v_mul_f32_e32 v29, 0x3fb8aa3b, v29
	v_mul_f32_e32 v30, 0x3fb8aa3b, v30
	v_exp_f32_e32 v28, v28
	v_exp_f32_e32 v29, v29
	v_exp_f32_e32 v30, v30
	s_nop 0
	v_add_f32_e32 v32, v28, v29
	v_add_f32_e32 v32, v30, v32
	v_rcp_f32_e32 v32, v32
	s_nop 0
	v_mul_f32_e32 v28, v28, v32
	v_mul_f32_e32 v29, v29, v32
	v_mul_f32_e32 v30, v30, v32
	s_waitcnt vmcnt(6)
; DI void st8(u16* dst, const float (&v)[8]) { *(u32x4*)dst = pack8(v); }
; DI void phase_merge(const Params& p) {
;     ...
;     const float l0 = LSE[(size_t)(0 * CT + lt) * 4 + h], l1 = LSE[(size_t)(1 * CT + lt) * 4 + h], l2 = LSE[(size_t)(2 * CT + lt) * 4 + h];
;     const float mx = fmaxf(l0, fmaxf(l1, l2));
;     float w0 = __expf(l0 - mx), w1 = __expf(l1 - mx), w2 = __expf(l2 - mx); const float inv = 1.f / (w0 + w1 + w2); w0 *= inv; w1 *= inv; w2 *= inv;
;     float a[8], b[8], c[8], o[8];
;     unpack8(*(const u32x4*)(AO + (size_t)(0 * CT + lt) * 512 + c8 * 8), a);
;     unpack8(*(const u32x4*)(AO + (size_t)(1 * CT + lt) * 512 + c8 * 8), b);
;     unpack8(*(const u32x4*)(AO + (size_t)(2 * CT + lt) * 512 + c8 * 8), c);
; #pragma unroll
;     for (int j = 0; j < 8; ++j) o[j] = w0 * a[j] + w1 * b[j] + w2 * c[j];
;     st8(BR0 + (size_t)lt * 512 + c8 * 8, o);
	v_lshlrev_b32_e32 v88, 16, v52
	v_and_b32_e32 v89, 0xffff0000, v52
	v_lshlrev_b32_e32 v90, 16, v56
	v_and_b32_e32 v91, 0xffff0000, v56
	v_lshlrev_b32_e32 v92, 16, v60
	v_and_b32_e32 v93, 0xffff0000, v60
	v_mul_f32_e32 v88, v28, v88
	v_mul_f32_e32 v89, v28, v89
	v_fmac_f32_e32 v88, v29, v90
	v_fmac_f32_e32 v89, v29, v91
	v_fmac_f32_e32 v88, v30, v92
	v_fmac_f32_e32 v89, v30, v93
	v_cvt_pk_bf16_f32 v52, v88, v89
	v_lshlrev_b32_e32 v88, 16, v53
	v_and_b32_e32 v89, 0xffff0000, v53
	v_lshlrev_b32_e32 v90, 16, v57
	v_and_b32_e32 v91, 0xffff0000, v57
	v_lshlrev_b32_e32 v92, 16, v61
	v_and_b32_e32 v93, 0xffff0000, v61
	v_mul_f32_e32 v88, v28, v88
	v_mul_f32_e32 v89, v28, v89
	v_fmac_f32_e32 v88, v29, v90
	v_fmac_f32_e32 v89, v29, v91
	v_fmac_f32_e32 v88, v30, v92
	v_fmac_f32_e32 v89, v30, v93
	v_cvt_pk_bf16_f32 v53, v88, v89
	v_lshlrev_b32_e32 v88, 16, v54
	v_and_b32_e32 v89, 0xffff0000, v54
	v_lshlrev_b32_e32 v90, 16, v58
	v_and_b32_e32 v91, 0xffff0000, v58
	v_lshlrev_b32_e32 v92, 16, v62
	v_and_b32_e32 v93, 0xffff0000, v62
	v_mul_f32_e32 v88, v28, v88
	v_mul_f32_e32 v89, v28, v89
	v_fmac_f32_e32 v88, v29, v90
	v_fmac_f32_e32 v89, v29, v91
	v_fmac_f32_e32 v88, v30, v92
	v_fmac_f32_e32 v89, v30, v93
	v_cvt_pk_bf16_f32 v54, v88, v89
	v_lshlrev_b32_e32 v88, 16, v55
	v_and_b32_e32 v89, 0xffff0000, v55
	v_lshlrev_b32_e32 v90, 16, v59
	v_and_b32_e32 v91, 0xffff0000, v59
	v_lshlrev_b32_e32 v92, 16, v63
	v_and_b32_e32 v93, 0xffff0000, v63
	v_mul_f32_e32 v88, v28, v88
	v_mul_f32_e32 v89, v28, v89
	v_fmac_f32_e32 v88, v29, v90
	v_fmac_f32_e32 v89, v29, v91
	v_fmac_f32_e32 v88, v30, v92
	v_fmac_f32_e32 v89, v30, v93
	v_cvt_pk_bf16_f32 v55, v88, v89
	v_add_u32_e32 v11, 0x200000, v10
	global_store_dwordx4 v11, v[52:55], s[26:27]
	v_max3_f32 v31, v22, v23, v24
	v_sub_f32_e32 v28, v22, v31
	v_sub_f32_e32 v29, v23, v31
	v_sub_f32_e32 v30, v24, v31
	v_mul_f32_e32 v28, 0x3fb8aa3b, v28
	v_mul_f32_e32 v29, 0x3fb8aa3b, v29
	v_mul_f32_e32 v30, 0x3fb8aa3b, v30
	v_exp_f32_e32 v28, v28
	v_exp_f32_e32 v29, v29
	v_exp_f32_e32 v30, v30
	s_nop 0
	v_add_f32_e32 v32, v28, v29
	v_add_f32_e32 v32, v30, v32
	v_rcp_f32_e32 v32, v32
	s_nop 0
	v_mul_f32_e32 v28, v28, v32
	v_mul_f32_e32 v29, v29, v32
	v_mul_f32_e32 v30, v30, v32
	s_waitcnt vmcnt(3)
	v_lshlrev_b32_e32 v88, 16, v64
	v_and_b32_e32 v89, 0xffff0000, v64
	v_lshlrev_b32_e32 v90, 16, v68
	v_and_b32_e32 v91, 0xffff0000, v68
	v_lshlrev_b32_e32 v92, 16, v72
	v_and_b32_e32 v93, 0xffff0000, v72
	v_mul_f32_e32 v88, v28, v88
	v_mul_f32_e32 v89, v28, v89
	v_fmac_f32_e32 v88, v29, v90
	v_fmac_f32_e32 v89, v29, v91
	v_fmac_f32_e32 v88, v30, v92
	v_fmac_f32_e32 v89, v30, v93
	v_cvt_pk_bf16_f32 v64, v88, v89
	v_lshlrev_b32_e32 v88, 16, v65
	v_and_b32_e32 v89, 0xffff0000, v65
	v_lshlrev_b32_e32 v90, 16, v69
	v_and_b32_e32 v91, 0xffff0000, v69
	v_lshlrev_b32_e32 v92, 16, v73
	v_and_b32_e32 v93, 0xffff0000, v73
	v_mul_f32_e32 v88, v28, v88
	v_mul_f32_e32 v89, v28, v89
	v_fmac_f32_e32 v88, v29, v90
	v_fmac_f32_e32 v89, v29, v91
	v_fmac_f32_e32 v88, v30, v92
	v_fmac_f32_e32 v89, v30, v93
	v_cvt_pk_bf16_f32 v65, v88, v89
	v_lshlrev_b32_e32 v88, 16, v66
	v_and_b32_e32 v89, 0xffff0000, v66
	v_lshlrev_b32_e32 v90, 16, v70
	v_and_b32_e32 v91, 0xffff0000, v70
	v_lshlrev_b32_e32 v92, 16, v74
	v_and_b32_e32 v93, 0xffff0000, v74
	v_mul_f32_e32 v88, v28, v88
	v_mul_f32_e32 v89, v28, v89
	v_fmac_f32_e32 v88, v29, v90
	v_fmac_f32_e32 v89, v29, v91
	v_fmac_f32_e32 v88, v30, v92
	v_fmac_f32_e32 v89, v30, v93
	v_cvt_pk_bf16_f32 v66, v88, v89
	v_lshlrev_b32_e32 v88, 16, v67
	v_and_b32_e32 v89, 0xffff0000, v67
	v_lshlrev_b32_e32 v90, 16, v71
	v_and_b32_e32 v91, 0xffff0000, v71
	v_lshlrev_b32_e32 v92, 16, v75
	v_and_b32_e32 v93, 0xffff0000, v75
	v_mul_f32_e32 v88, v28, v88
	v_mul_f32_e32 v89, v28, v89
	v_fmac_f32_e32 v88, v29, v90
	v_fmac_f32_e32 v89, v29, v91
	v_fmac_f32_e32 v88, v30, v92
	v_fmac_f32_e32 v89, v30, v93
	v_cvt_pk_bf16_f32 v67, v88, v89
	v_add_u32_e32 v11, 0x400000, v10
	global_store_dwordx4 v11, v[64:67], s[26:27]
	v_max3_f32 v31, v25, v26, v27
	v_sub_f32_e32 v28, v25, v31
	v_sub_f32_e32 v29, v26, v31
	v_sub_f32_e32 v30, v27, v31
	v_mul_f32_e32 v28, 0x3fb8aa3b, v28
	v_mul_f32_e32 v29, 0x3fb8aa3b, v29
	v_mul_f32_e32 v30, 0x3fb8aa3b, v30
	v_exp_f32_e32 v28, v28
	v_exp_f32_e32 v29, v29
	v_exp_f32_e32 v30, v30
	s_nop 0
	v_add_f32_e32 v32, v28, v29
	v_add_f32_e32 v32, v30, v32
	v_rcp_f32_e32 v32, v32
	s_nop 0
	v_mul_f32_e32 v28, v28, v32
	v_mul_f32_e32 v29, v29, v32
	v_mul_f32_e32 v30, v30, v32
	s_waitcnt vmcnt(0)
; DI int TID() { int t = (int)__builtin_amdgcn_workitem_id_x(); asm volatile("" : "+v"(t)); return t; }
; DI int BID() { int b = (int)__builtin_amdgcn_workgroup_id_x(); asm volatile("" : "+s"(b)); return b; }
; DI void st8(u16* dst, const float (&v)[8]) { *(u32x4*)dst = pack8(v); }
; DI void phase_merge(const Params& p) {
;     ...
;   for (int i = BID() * 256 + TID(); i < CT * 64; i += gsz) {
;     const int lt = i >> 6, c8 = i & 63, h = c8 >> 4;
;     const float l0 = LSE[(size_t)(0 * CT + lt) * 4 + h], l1 = LSE[(size_t)(1 * CT + lt) * 4 + h], l2 = LSE[(size_t)(2 * CT + lt) * 4 + h];
;     const float mx = fmaxf(l0, fmaxf(l1, l2));
;     float w0 = __expf(l0 - mx), w1 = __expf(l1 - mx), w2 = __expf(l2 - mx); const float inv = 1.f / (w0 + w1 + w2); w0 *= inv; w1 *= inv; w2 *= inv;
;     float a[8], b[8], c[8], o[8];
;     unpack8(*(const u32x4*)(AO + (size_t)(0 * CT + lt) * 512 + c8 * 8), a);
;     unpack8(*(const u32x4*)(AO + (size_t)(1 * CT + lt) * 512 + c8 * 8), b);
;     unpack8(*(const u32x4*)(AO + (size_t)(2 * CT + lt) * 512 + c8 * 8), c);
; #pragma unroll
;     for (int j = 0; j < 8; ++j) o[j] = w0 * a[j] + w1 * b[j] + w2 * c[j];
;     st8(BR0 + (size_t)lt * 512 + c8 * 8, o);
;   }
	v_lshlrev_b32_e32 v88, 16, v76
	v_and_b32_e32 v89, 0xffff0000, v76
	v_lshlrev_b32_e32 v90, 16, v80
	v_and_b32_e32 v91, 0xffff0000, v80
	v_lshlrev_b32_e32 v92, 16, v84
	v_and_b32_e32 v93, 0xffff0000, v84
	v_mul_f32_e32 v88, v28, v88
	v_mul_f32_e32 v89, v28, v89
	v_fmac_f32_e32 v88, v29, v90
	v_fmac_f32_e32 v89, v29, v91
	v_fmac_f32_e32 v88, v30, v92
	v_fmac_f32_e32 v89, v30, v93
	v_cvt_pk_bf16_f32 v76, v88, v89
	v_lshlrev_b32_e32 v88, 16, v77
	v_and_b32_e32 v89, 0xffff0000, v77
	v_lshlrev_b32_e32 v90, 16, v81
	v_and_b32_e32 v91, 0xffff0000, v81
	v_lshlrev_b32_e32 v92, 16, v85
	v_and_b32_e32 v93, 0xffff0000, v85
	v_mul_f32_e32 v88, v28, v88
	v_mul_f32_e32 v89, v28, v89
	v_fmac_f32_e32 v88, v29, v90
	v_fmac_f32_e32 v89, v29, v91
	v_fmac_f32_e32 v88, v30, v92
	v_fmac_f32_e32 v89, v30, v93
	v_cvt_pk_bf16_f32 v77, v88, v89
	v_lshlrev_b32_e32 v88, 16, v78
	v_and_b32_e32 v89, 0xffff0000, v78
	v_lshlrev_b32_e32 v90, 16, v82
	v_and_b32_e32 v91, 0xffff0000, v82
	v_lshlrev_b32_e32 v92, 16, v86
	v_and_b32_e32 v93, 0xffff0000, v86
	v_mul_f32_e32 v88, v28, v88
	v_mul_f32_e32 v89, v28, v89
	v_fmac_f32_e32 v88, v29, v90
	v_fmac_f32_e32 v89, v29, v91
	v_fmac_f32_e32 v88, v30, v92
	v_fmac_f32_e32 v89, v30, v93
	v_cvt_pk_bf16_f32 v78, v88, v89
	v_lshlrev_b32_e32 v88, 16, v79
	v_and_b32_e32 v89, 0xffff0000, v79
	v_lshlrev_b32_e32 v90, 16, v83
	v_and_b32_e32 v91, 0xffff0000, v83
	v_lshlrev_b32_e32 v92, 16, v87
	v_and_b32_e32 v93, 0xffff0000, v87
	v_mul_f32_e32 v88, v28, v88
	v_mul_f32_e32 v89, v28, v89
	v_fmac_f32_e32 v88, v29, v90
	v_fmac_f32_e32 v89, v29, v91
	v_fmac_f32_e32 v88, v30, v92
	v_fmac_f32_e32 v89, v30, v93
	v_cvt_pk_bf16_f32 v79, v88, v89
	v_add_u32_e32 v11, 0x600000, v10
	global_store_dwordx4 v11, v[76:79], s[26:27]
	v_add_u32_e32 v11, 0x20000, v9
	global_load_dword v16, v11, s[16:17]
	v_add_u32_e32 v12, 0x60000, v9
	global_load_dword v17, v12, s[16:17]
	v_add_u32_e32 v11, 0xa0000, v9
	global_load_dword v18, v11, s[16:17]
	v_add_u32_e32 v12, 0x28000, v9
	global_load_dword v19, v12, s[16:17]
	v_add_u32_e32 v11, 0x68000, v9
	global_load_dword v20, v11, s[16:17]
	v_add_u32_e32 v12, 0xa8000, v9
	global_load_dword v21, v12, s[16:17]
	v_add_u32_e32 v11, 0x30000, v9
	global_load_dword v22, v11, s[16:17]
	v_add_u32_e32 v12, 0x70000, v9
	global_load_dword v23, v12, s[16:17]
	v_add_u32_e32 v11, 0xb0000, v9
	global_load_dword v24, v11, s[16:17]
	v_add_u32_e32 v12, 0x38000, v9
	global_load_dword v25, v12, s[16:17]
	v_add_u32_e32 v11, 0x78000, v9
	global_load_dword v26, v11, s[16:17]
	v_add_u32_e32 v12, 0xb8000, v9
	global_load_dword v27, v12, s[16:17]
	v_add_u32_e32 v11, 0x800000, v10
	global_load_dwordx4 v[40:43], v11, s[22:23]
	v_add_u32_e32 v12, 0x1800000, v10
	global_load_dwordx4 v[44:47], v12, s[22:23]
	v_add_u32_e32 v11, 0x2800000, v10
	global_load_dwordx4 v[48:51], v11, s[22:23]
	v_add_u32_e32 v12, 0xa00000, v10
	global_load_dwordx4 v[52:55], v12, s[22:23]
	v_add_u32_e32 v11, 0x1a00000, v10
	global_load_dwordx4 v[56:59], v11, s[22:23]
	v_add_u32_e32 v12, 0x2a00000, v10
	global_load_dwordx4 v[60:63], v12, s[22:23]
	v_add_u32_e32 v11, 0xc00000, v10
	global_load_dwordx4 v[64:67], v11, s[22:23]
	v_add_u32_e32 v12, 0x1c00000, v10
	global_load_dwordx4 v[68:71], v12, s[22:23]
	v_add_u32_e32 v11, 0x2c00000, v10
	global_load_dwordx4 v[72:75], v11, s[22:23]
	v_add_u32_e32 v12, 0xe00000, v10
	global_load_dwordx4 v[76:79], v12, s[22:23]
	v_add_u32_e32 v11, 0x1e00000, v10
	global_load_dwordx4 v[80:83], v11, s[22:23]
	v_add_u32_e32 v12, 0x2e00000, v10
	global_load_dwordx4 v[84:87], v12, s[22:23]
	s_waitcnt vmcnt(12)
	v_max3_f32 v31, v16, v17, v18
	v_sub_f32_e32 v28, v16, v31
	v_sub_f32_e32 v29, v17, v31
	v_sub_f32_e32 v30, v18, v31
	v_mul_f32_e32 v28, 0x3fb8aa3b, v28
	v_mul_f32_e32 v29, 0x3fb8aa3b, v29
	v_mul_f32_e32 v30, 0x3fb8aa3b, v30
	v_exp_f32_e32 v28, v28
	v_exp_f32_e32 v29, v29
	v_exp_f32_e32 v30, v30
	s_nop 0
	v_add_f32_e32 v32, v28, v29
	v_add_f32_e32 v32, v30, v32
	v_rcp_f32_e32 v32, v32
	s_nop 0
	v_mul_f32_e32 v28, v28, v32
	v_mul_f32_e32 v29, v29, v32
	v_mul_f32_e32 v30, v30, v32
	s_waitcnt vmcnt(9)
	v_lshlrev_b32_e32 v88, 16, v40
	v_and_b32_e32 v89, 0xffff0000, v40
	v_lshlrev_b32_e32 v90, 16, v44
	v_and_b32_e32 v91, 0xffff0000, v44
	v_lshlrev_b32_e32 v92, 16, v48
	v_and_b32_e32 v93, 0xffff0000, v48
	v_mul_f32_e32 v88, v28, v88
	v_mul_f32_e32 v89, v28, v89
	v_fmac_f32_e32 v88, v29, v90
	v_fmac_f32_e32 v89, v29, v91
	v_fmac_f32_e32 v88, v30, v92
	v_fmac_f32_e32 v89, v30, v93
	v_cvt_pk_bf16_f32 v40, v88, v89
	v_lshlrev_b32_e32 v88, 16, v41
	v_and_b32_e32 v89, 0xffff0000, v41
	v_lshlrev_b32_e32 v90, 16, v45
	v_and_b32_e32 v91, 0xffff0000, v45
	v_lshlrev_b32_e32 v92, 16, v49
	v_and_b32_e32 v93, 0xffff0000, v49
	v_mul_f32_e32 v88, v28, v88
	v_mul_f32_e32 v89, v28, v89
	v_fmac_f32_e32 v88, v29, v90
	v_fmac_f32_e32 v89, v29, v91
	v_fmac_f32_e32 v88, v30, v92
	v_fmac_f32_e32 v89, v30, v93
	v_cvt_pk_bf16_f32 v41, v88, v89
	v_lshlrev_b32_e32 v88, 16, v42
	v_and_b32_e32 v89, 0xffff0000, v42
	v_lshlrev_b32_e32 v90, 16, v46
	v_and_b32_e32 v91, 0xffff0000, v46
	v_lshlrev_b32_e32 v92, 16, v50
	v_and_b32_e32 v93, 0xffff0000, v50
	v_mul_f32_e32 v88, v28, v88
	v_mul_f32_e32 v89, v28, v89
	v_fmac_f32_e32 v88, v29, v90
	v_fmac_f32_e32 v89, v29, v91
	v_fmac_f32_e32 v88, v30, v92
	v_fmac_f32_e32 v89, v30, v93
	v_cvt_pk_bf16_f32 v42, v88, v89
	v_lshlrev_b32_e32 v88, 16, v43
	v_and_b32_e32 v89, 0xffff0000, v43
	v_lshlrev_b32_e32 v90, 16, v47
	v_and_b32_e32 v91, 0xffff0000, v47
	v_lshlrev_b32_e32 v92, 16, v51
	v_and_b32_e32 v93, 0xffff0000, v51
	v_mul_f32_e32 v88, v28, v88
	v_mul_f32_e32 v89, v28, v89
	v_fmac_f32_e32 v88, v29, v90
	v_fmac_f32_e32 v89, v29, v91
	v_fmac_f32_e32 v88, v30, v92
	v_fmac_f32_e32 v89, v30, v93
	v_cvt_pk_bf16_f32 v43, v88, v89
	v_add_u32_e32 v11, 0x800000, v10
	global_store_dwordx4 v11, v[40:43], s[26:27]
	v_max3_f32 v31, v19, v20, v21
	v_sub_f32_e32 v28, v19, v31
	v_sub_f32_e32 v29, v20, v31
	v_sub_f32_e32 v30, v21, v31
	v_mul_f32_e32 v28, 0x3fb8aa3b, v28
	v_mul_f32_e32 v29, 0x3fb8aa3b, v29
	v_mul_f32_e32 v30, 0x3fb8aa3b, v30
	v_exp_f32_e32 v28, v28
	v_exp_f32_e32 v29, v29
	v_exp_f32_e32 v30, v30
	s_nop 0
	v_add_f32_e32 v32, v28, v29
	v_add_f32_e32 v32, v30, v32
	v_rcp_f32_e32 v32, v32
	s_nop 0
	v_mul_f32_e32 v28, v28, v32
	v_mul_f32_e32 v29, v29, v32
	v_mul_f32_e32 v30, v30, v32
	s_waitcnt vmcnt(6)
; DI void st8(u16* dst, const float (&v)[8]) { *(u32x4*)dst = pack8(v); }
; DI void phase_merge(const Params& p) {
;     ...
;     const float l0 = LSE[(size_t)(0 * CT + lt) * 4 + h], l1 = LSE[(size_t)(1 * CT + lt) * 4 + h], l2 = LSE[(size_t)(2 * CT + lt) * 4 + h];
;     const float mx = fmaxf(l0, fmaxf(l1, l2));
;     float w0 = __expf(l0 - mx), w1 = __expf(l1 - mx), w2 = __expf(l2 - mx); const float inv = 1.f / (w0 + w1 + w2); w0 *= inv; w1 *= inv; w2 *= inv;
;     float a[8], b[8], c[8], o[8];
;     unpack8(*(const u32x4*)(AO + (size_t)(0 * CT + lt) * 512 + c8 * 8), a);
;     unpack8(*(const u32x4*)(AO + (size_t)(1 * CT + lt) * 512 + c8 * 8), b);
;     unpack8(*(const u32x4*)(AO + (size_t)(2 * CT + lt) * 512 + c8 * 8), c);
; #pragma unroll
;     for (int j = 0; j < 8; ++j) o[j] = w0 * a[j] + w1 * b[j] + w2 * c[j];
;     st8(BR0 + (size_t)lt * 512 + c8 * 8, o);
	v_lshlrev_b32_e32 v88, 16, v52
	v_and_b32_e32 v89, 0xffff0000, v52
	v_lshlrev_b32_e32 v90, 16, v56
	v_and_b32_e32 v91, 0xffff0000, v56
	v_lshlrev_b32_e32 v92, 16, v60
	v_and_b32_e32 v93, 0xffff0000, v60
	v_mul_f32_e32 v88, v28, v88
	v_mul_f32_e32 v89, v28, v89
	v_fmac_f32_e32 v88, v29, v90
	v_fmac_f32_e32 v89, v29, v91
	v_fmac_f32_e32 v88, v30, v92
	v_fmac_f32_e32 v89, v30, v93
	v_cvt_pk_bf16_f32 v52, v88, v89
	v_lshlrev_b32_e32 v88, 16, v53
	v_and_b32_e32 v89, 0xffff0000, v53
	v_lshlrev_b32_e32 v90, 16, v57
	v_and_b32_e32 v91, 0xffff0000, v57
	v_lshlrev_b32_e32 v92, 16, v61
	v_and_b32_e32 v93, 0xffff0000, v61
	v_mul_f32_e32 v88, v28, v88
	v_mul_f32_e32 v89, v28, v89
	v_fmac_f32_e32 v88, v29, v90
	v_fmac_f32_e32 v89, v29, v91
	v_fmac_f32_e32 v88, v30, v92
	v_fmac_f32_e32 v89, v30, v93
	v_cvt_pk_bf16_f32 v53, v88, v89
	v_lshlrev_b32_e32 v88, 16, v54
	v_and_b32_e32 v89, 0xffff0000, v54
	v_lshlrev_b32_e32 v90, 16, v58
	v_and_b32_e32 v91, 0xffff0000, v58
	v_lshlrev_b32_e32 v92, 16, v62
	v_and_b32_e32 v93, 0xffff0000, v62
	v_mul_f32_e32 v88, v28, v88
	v_mul_f32_e32 v89, v28, v89
	v_fmac_f32_e32 v88, v29, v90
	v_fmac_f32_e32 v89, v29, v91
	v_fmac_f32_e32 v88, v30, v92
	v_fmac_f32_e32 v89, v30, v93
	v_cvt_pk_bf16_f32 v54, v88, v89
	v_lshlrev_b32_e32 v88, 16, v55
	v_and_b32_e32 v89, 0xffff0000, v55
	v_lshlrev_b32_e32 v90, 16, v59
	v_and_b32_e32 v91, 0xffff0000, v59
	v_lshlrev_b32_e32 v92, 16, v63
	v_and_b32_e32 v93, 0xffff0000, v63
	v_mul_f32_e32 v88, v28, v88
	v_mul_f32_e32 v89, v28, v89
	v_fmac_f32_e32 v88, v29, v90
	v_fmac_f32_e32 v89, v29, v91
	v_fmac_f32_e32 v88, v30, v92
	v_fmac_f32_e32 v89, v30, v93
	v_cvt_pk_bf16_f32 v55, v88, v89
	v_add_u32_e32 v11, 0xa00000, v10
	global_store_dwordx4 v11, v[52:55], s[26:27]
	v_max3_f32 v31, v22, v23, v24
	v_sub_f32_e32 v28, v22, v31
	v_sub_f32_e32 v29, v23, v31
	v_sub_f32_e32 v30, v24, v31
	v_mul_f32_e32 v28, 0x3fb8aa3b, v28
	v_mul_f32_e32 v29, 0x3fb8aa3b, v29
	v_mul_f32_e32 v30, 0x3fb8aa3b, v30
	v_exp_f32_e32 v28, v28
	v_exp_f32_e32 v29, v29
	v_exp_f32_e32 v30, v30
	s_nop 0
	v_add_f32_e32 v32, v28, v29
	v_add_f32_e32 v32, v30, v32
	v_rcp_f32_e32 v32, v32
	s_nop 0
	v_mul_f32_e32 v28, v28, v32
	v_mul_f32_e32 v29, v29, v32
	v_mul_f32_e32 v30, v30, v32
	s_waitcnt vmcnt(3)
	v_lshlrev_b32_e32 v88, 16, v64
	v_and_b32_e32 v89, 0xffff0000, v64
	v_lshlrev_b32_e32 v90, 16, v68
	v_and_b32_e32 v91, 0xffff0000, v68
	v_lshlrev_b32_e32 v92, 16, v72
	v_and_b32_e32 v93, 0xffff0000, v72
	v_mul_f32_e32 v88, v28, v88
	v_mul_f32_e32 v89, v28, v89
	v_fmac_f32_e32 v88, v29, v90
	v_fmac_f32_e32 v89, v29, v91
	v_fmac_f32_e32 v88, v30, v92
	v_fmac_f32_e32 v89, v30, v93
	v_cvt_pk_bf16_f32 v64, v88, v89
	v_lshlrev_b32_e32 v88, 16, v65
	v_and_b32_e32 v89, 0xffff0000, v65
	v_lshlrev_b32_e32 v90, 16, v69
	v_and_b32_e32 v91, 0xffff0000, v69
	v_lshlrev_b32_e32 v92, 16, v73
	v_and_b32_e32 v93, 0xffff0000, v73
	v_mul_f32_e32 v88, v28, v88
	v_mul_f32_e32 v89, v28, v89
	v_fmac_f32_e32 v88, v29, v90
	v_fmac_f32_e32 v89, v29, v91
	v_fmac_f32_e32 v88, v30, v92
	v_fmac_f32_e32 v89, v30, v93
	v_cvt_pk_bf16_f32 v65, v88, v89
	v_lshlrev_b32_e32 v88, 16, v66
	v_and_b32_e32 v89, 0xffff0000, v66
	v_lshlrev_b32_e32 v90, 16, v70
	v_and_b32_e32 v91, 0xffff0000, v70
	v_lshlrev_b32_e32 v92, 16, v74
	v_and_b32_e32 v93, 0xffff0000, v74
	v_mul_f32_e32 v88, v28, v88
	v_mul_f32_e32 v89, v28, v89
	v_fmac_f32_e32 v88, v29, v90
	v_fmac_f32_e32 v89, v29, v91
	v_fmac_f32_e32 v88, v30, v92
	v_fmac_f32_e32 v89, v30, v93
	v_cvt_pk_bf16_f32 v66, v88, v89
	v_lshlrev_b32_e32 v88, 16, v67
	v_and_b32_e32 v89, 0xffff0000, v67
	v_lshlrev_b32_e32 v90, 16, v71
	v_and_b32_e32 v91, 0xffff0000, v71
	v_lshlrev_b32_e32 v92, 16, v75
	v_and_b32_e32 v93, 0xffff0000, v75
	v_mul_f32_e32 v88, v28, v88
	v_mul_f32_e32 v89, v28, v89
	v_fmac_f32_e32 v88, v29, v90
	v_fmac_f32_e32 v89, v29, v91
	v_fmac_f32_e32 v88, v30, v92
	v_fmac_f32_e32 v89, v30, v93
	v_cvt_pk_bf16_f32 v67, v88, v89
	v_add_u32_e32 v11, 0xc00000, v10
	global_store_dwordx4 v11, v[64:67], s[26:27]
	v_max3_f32 v31, v25, v26, v27
	v_sub_f32_e32 v28, v25, v31
	v_sub_f32_e32 v29, v26, v31
	v_sub_f32_e32 v30, v27, v31
	v_mul_f32_e32 v28, 0x3fb8aa3b, v28
	v_mul_f32_e32 v29, 0x3fb8aa3b, v29
	v_mul_f32_e32 v30, 0x3fb8aa3b, v30
	v_exp_f32_e32 v28, v28
	v_exp_f32_e32 v29, v29
	v_exp_f32_e32 v30, v30
	s_nop 0
	v_add_f32_e32 v32, v28, v29
	v_add_f32_e32 v32, v30, v32
	v_rcp_f32_e32 v32, v32
	s_nop 0
	v_mul_f32_e32 v28, v28, v32
	v_mul_f32_e32 v29, v29, v32
	v_mul_f32_e32 v30, v30, v32
	s_waitcnt vmcnt(0)
	v_lshlrev_b32_e32 v88, 16, v76
	v_and_b32_e32 v89, 0xffff0000, v76
	v_lshlrev_b32_e32 v90, 16, v80
	v_and_b32_e32 v91, 0xffff0000, v80
	v_lshlrev_b32_e32 v92, 16, v84
	v_and_b32_e32 v93, 0xffff0000, v84
	v_mul_f32_e32 v88, v28, v88
	v_mul_f32_e32 v89, v28, v89
	v_fmac_f32_e32 v88, v29, v90
	v_fmac_f32_e32 v89, v29, v91
	v_fmac_f32_e32 v88, v30, v92
	v_fmac_f32_e32 v89, v30, v93
	v_cvt_pk_bf16_f32 v76, v88, v89
	v_lshlrev_b32_e32 v88, 16, v77
	v_and_b32_e32 v89, 0xffff0000, v77
	v_lshlrev_b32_e32 v90, 16, v81
	v_and_b32_e32 v91, 0xffff0000, v81
	v_lshlrev_b32_e32 v92, 16, v85
	v_and_b32_e32 v93, 0xffff0000, v85
	v_mul_f32_e32 v88, v28, v88
	v_mul_f32_e32 v89, v28, v89
	v_fmac_f32_e32 v88, v29, v90
	v_fmac_f32_e32 v89, v29, v91
	v_fmac_f32_e32 v88, v30, v92
	v_fmac_f32_e32 v89, v30, v93
	v_cvt_pk_bf16_f32 v77, v88, v89
	v_lshlrev_b32_e32 v88, 16, v78
	v_and_b32_e32 v89, 0xffff0000, v78
	v_lshlrev_b32_e32 v90, 16, v82
	v_and_b32_e32 v91, 0xffff0000, v82
	v_lshlrev_b32_e32 v92, 16, v86
	v_and_b32_e32 v93, 0xffff0000, v86
	v_mul_f32_e32 v88, v28, v88
	v_mul_f32_e32 v89, v28, v89
	v_fmac_f32_e32 v88, v29, v90
	v_fmac_f32_e32 v89, v29, v91
	v_fmac_f32_e32 v88, v30, v92
	v_fmac_f32_e32 v89, v30, v93
	v_cvt_pk_bf16_f32 v78, v88, v89
	v_lshlrev_b32_e32 v88, 16, v79
	v_and_b32_e32 v89, 0xffff0000, v79
	v_lshlrev_b32_e32 v90, 16, v83
	v_and_b32_e32 v91, 0xffff0000, v83
	v_lshlrev_b32_e32 v92, 16, v87
	v_and_b32_e32 v93, 0xffff0000, v87
	v_mul_f32_e32 v88, v28, v88
	v_mul_f32_e32 v89, v28, v89
	v_fmac_f32_e32 v88, v29, v90
	v_fmac_f32_e32 v89, v29, v91
	v_fmac_f32_e32 v88, v30, v92
	v_fmac_f32_e32 v89, v30, v93
	v_cvt_pk_bf16_f32 v79, v88, v89
	v_add_u32_e32 v11, 0xe00000, v10
	global_store_dwordx4 v11, v[76:79], s[26:27]

; DI void st8(u16* dst, const float (&v)[8]) { *(u32x4*)dst = pack8(v); }
; DI RowSS rowss_load(const float* ps, int m0) { const int tid = TID(); const float* q = ps + (size_t)(m0 + (tid >> 1)) * 16 + (tid & 1) * 8; RowSS r; r.a = *(const f32x4*)q; r.b = *(const f32x4*)(q + 4); return r; }
; DI void tile_inproj(const Params& p, int l, const Chunk& ck, int tile, int next, PF& pf, char* smem) {
;   float* Cs = (float*)smem; float* rinv_s = (float*)(smem + SMEM_CS);
;   const int mi = tile & (MTN - 1), nj = tile >> MTS; const int ni = (nj < 45) ? nj : 69; const int m0 = mi * 128;
;   const u16* Ap; const u16* Wt; inproj_ptrs(p, l, tile, Ap, Wt);
;   f32x16 acc[2][2]; zero_acc(acc);
;   const RowSS rss = rowss_load((const float*)(p.ws + OFF_PSIN), m0);
;   gemm_run<16>(pf, Ap, 1024, Wt, acc, smem);
;     ...
;   if (ni < 24 || (ni >= 41 && ni < 45)) {
;     const float* gain; u16* dst; float scale;
;     if (ni < 24) {
;       const int g = (ni % 12) >> 2, h = ni & 3; const bool isq = ni < 12; const int dsh = 2 * g, d = 1 << dsh, Lg = S >> dsh;
;       gain = (const float*)(p.ws + OFF_GAINS) + (isq ? GN_DQ : GN_DK) + ((l * 3 + g) * 4 + h) * 128;
;       const int pp = (t & (d - 1)) * Lg + (t >> dsh);
;       dst = (u16*)(p.ws + (isq ? OFF_QD : OFF_KD)) + ((size_t)(g * CT + bl * S + pp)) * 512 + h * 128 + half * 64;
;       scale = isq ? QS128 : 1.f;
;     } else {
;       const int h = ni - 41; gain = (const float*)(p.ws + OFF_GAINS) + GN_MEMQ + l * 128;
;       dst = (u16*)(p.ws + OFF_MQ) + (size_t)lt * 512 + h * 128 + half * 64; scale = QS128;
;     }
;     float ssq = 0.f;
; #pragma unroll
;     for (int c8 = 0; c8 < 8; ++c8) { cs_ld8(Cs, row, half * 64 + c8 * 8, v);
; #pragma unroll
;       for (int j = 0; j < 8; ++j) ssq += v[j] * v[j]; }
;     ssq *= rinv * rinv; ssq += __shfl_xor(ssq, 1);
;     const float rn = rsqrtf(ssq * (1.f / 128.f) + EPS) * rinv * scale;
; #pragma unroll
;     for (int c8 = 0; c8 < 8; ++c8) { cs_ld8(Cs, row, half * 64 + c8 * 8, v);
; #pragma unroll
;       for (int j = 0; j < 8; ++j) v[j] = v[j] * rn * gain[half * 64 + c8 * 8 + j];
;       st8(dst + c8 * 8, v); }
;   } else if (ni < 36) {
.Linp_nokr:
	s_barrier
	s_mov_b32 s15, 0
	s_cmp_lt_u32 s30, 24
	s_cbranch_scc1 .Linp_dirk
	s_cmp_gt_u32 s30, 35
	s_cbranch_scc1 .Linp_dirk
	v_mov_b32_e32 v2, 0
	v_mov_b32_e32 v3, 0
	v_mov_b32_e32 v4, 0
	v_mov_b32_e32 v5, 0
	v_mov_b32_e32 v6, 0
	v_mov_b32_e32 v7, 0
	v_mov_b32_e32 v8, 0
	v_mov_b32_e32 v9, 0
	v_mov_b32_e32 v10, 0
	v_mov_b32_e32 v11, 0
	v_mov_b32_e32 v12, 0
	v_mov_b32_e32 v13, 0
	v_mov_b32_e32 v14, 0
	v_mov_b32_e32 v15, 0
	v_mov_b32_e32 v16, 0
	v_mov_b32_e32 v17, 0
	v_mov_b32_e32 v18, 0
	v_mov_b32_e32 v19, 0
	v_mov_b32_e32 v20, 0
	v_mov_b32_e32 v21, 0
	v_mov_b32_e32 v22, 0
	v_mov_b32_e32 v23, 0
	v_mov_b32_e32 v24, 0
	v_mov_b32_e32 v25, 0
	v_mov_b32_e32 v26, 0
	v_mov_b32_e32 v27, 0
	v_mov_b32_e32 v28, 0
	v_mov_b32_e32 v29, 0
	v_mov_b32_e32 v30, 0
	v_mov_b32_e32 v31, 0
	v_mov_b32_e32 v32, 0
	v_mov_b32_e32 v33, 0
	v_mov_b32_e32 v34, 0
	v_mov_b32_e32 v35, 0
	v_mov_b32_e32 v36, 0
	v_mov_b32_e32 v37, 0
	v_mov_b32_e32 v38, 0
	v_mov_b32_e32 v39, 0
	v_mov_b32_e32 v40, 0
	v_mov_b32_e32 v41, 0
	v_mov_b32_e32 v42, 0
	v_mov_b32_e32 v43, 0
	v_mov_b32_e32 v44, 0
	v_mov_b32_e32 v45, 0
	v_mov_b32_e32 v46, 0
	v_mov_b32_e32 v47, 0
	v_mov_b32_e32 v48, 0
	v_mov_b32_e32 v49, 0
	v_mov_b32_e32 v50, 0
	v_mov_b32_e32 v51, 0
	v_mov_b32_e32 v52, 0
	v_mov_b32_e32 v53, 0
	v_mov_b32_e32 v54, 0
	v_mov_b32_e32 v55, 0
	v_mov_b32_e32 v56, 0
	v_mov_b32_e32 v57, 0
	v_mov_b32_e32 v58, 0
	v_mov_b32_e32 v59, 0
	v_mov_b32_e32 v60, 0
	v_mov_b32_e32 v61, 0
	v_mov_b32_e32 v62, 0
	v_mov_b32_e32 v63, 0
	v_mov_b32_e32 v64, 0
	v_mov_b32_e32 v65, 0
	v_mov_b32_e32 v74, 0
	v_mov_b32_e32 v75, 0
	v_mov_b32_e32 v76, 0
	v_mov_b32_e32 v77, 0
	v_mov_b32_e32 v78, 0
	v_mov_b32_e32 v79, 0
	v_mov_b32_e32 v80, 0
	v_mov_b32_e32 v81, 0
	v_mov_b32_e32 v82, 0
	v_mov_b32_e32 v83, 0
	v_mov_b32_e32 v84, 0
	v_mov_b32_e32 v85, 0
	v_mov_b32_e32 v86, 0
	v_mov_b32_e32 v87, 0
	v_mov_b32_e32 v88, 0
	v_mov_b32_e32 v89, 0
	v_mov_b32_e32 v90, 0
	v_mov_b32_e32 v91, 0
	v_mov_b32_e32 v92, 0
	v_mov_b32_e32 v93, 0
	v_mov_b32_e32 v94, 0
	v_mov_b32_e32 v95, 0
	v_mov_b32_e32 v96, 0
	v_mov_b32_e32 v97, 0
	v_mov_b32_e32 v98, 0
	v_mov_b32_e32 v99, 0
	v_mov_b32_e32 v100, 0
	v_mov_b32_e32 v101, 0
	v_mov_b32_e32 v102, 0
	v_mov_b32_e32 v103, 0
	v_mov_b32_e32 v104, 0
	v_mov_b32_e32 v105, 0
	v_mov_b32_e32 v106, 0
	v_mov_b32_e32 v107, 0
	v_mov_b32_e32 v108, 0
	v_mov_b32_e32 v109, 0
	v_mov_b32_e32 v110, 0
	v_mov_b32_e32 v111, 0
	v_mov_b32_e32 v112, 0
	v_mov_b32_e32 v113, 0
	v_mov_b32_e32 v114, 0
	v_mov_b32_e32 v115, 0
	v_mov_b32_e32 v116, 0
	v_mov_b32_e32 v117, 0
	v_mov_b32_e32 v118, 0
	v_mov_b32_e32 v119, 0
	v_mov_b32_e32 v120, 0
	v_mov_b32_e32 v121, 0
	v_mov_b32_e32 v208, 0
	v_mov_b32_e32 v209, 0
	v_mov_b32_e32 v210, 0
	v_mov_b32_e32 v211, 0
	v_mov_b32_e32 v212, 0
	v_mov_b32_e32 v213, 0
	v_mov_b32_e32 v214, 0
	v_mov_b32_e32 v215, 0
	v_mov_b32_e32 v216, 0
	v_mov_b32_e32 v217, 0
	v_mov_b32_e32 v218, 0
	v_mov_b32_e32 v219, 0
	v_mov_b32_e32 v220, 0
	v_mov_b32_e32 v221, 0
	v_mov_b32_e32 v222, 0
	v_mov_b32_e32 v223, 0
	s_add_u32 m0, s46, 0x0
	s_nop 0
	global_load_lds_dwordx4 v138, s[48:49]
	global_load_lds_dwordx4 v139, s[48:49] offset:1024
	s_add_u32 m0, s47, 0x0
	s_nop 0
	global_load_lds_dwordx4 v140, s[50:51]
	global_load_lds_dwordx4 v141, s[50:51] offset:1024
	global_load_lds_dwordx4 v142, s[50:51] offset:2048
	global_load_lds_dwordx4 v143, s[50:51] offset:3072
	s_add_u32 m0, s46, 0x6000
	s_add_u32 s48, s48, 0x100000
	s_addc_u32 s49, s49, 0
	global_load_lds_dwordx4 v138, s[48:49]
	global_load_lds_dwordx4 v139, s[48:49] offset:1024
	s_add_u32 m0, s47, 0x6000
	s_add_u32 s50, s50, s13
	s_addc_u32 s51, s51, 0
	global_load_lds_dwordx4 v140, s[50:51]
	global_load_lds_dwordx4 v141, s[50:51] offset:1024
	global_load_lds_dwordx4 v142, s[50:51] offset:2048
	global_load_lds_dwordx4 v143, s[50:51] offset:3072
	s_mov_b32 s12, 10

; #define BLOAD(A_, B_, kt) do { _Pragma("unroll") for (int i = 0; i < 4; ++i) { \
;     A_[i] = *(const u32x4*)((const char*)Ap + (aoff + (unsigned)(32 * i * lda + (kt) * 64) * 2u)); B_[i] = *(const u32x4*)((const char*)Wt + (woff + (unsigned)(32 * i * K + (kt) * 64) * 2u)); } } while (0)
; #define BLOAD(A_, B_, kt) do { _Pragma("unroll") for (int i = 0; i < 4; ++i) { \
;     A_[i] = *(const u32x4*)((const char*)Ap + (aoff + (unsigned)(32 * i * lda + (kt) * 64) * 2u)); B_[i] = *(const u32x4*)((const char*)Wt + (woff + (unsigned)(32 * i * K + (kt) * 64) * 2u)); } } while (0)
; #define BSTORE(A_, B_, buf) do { _Pragma("unroll") for (int i = 0; i < 4; ++i) { \
;     *(u32x4*)&As[(buf) * GBUF + (srow + 32 * i) * LDT + sc8] = A_[i]; \
;     *(u32x4*)&Bs[(buf) * GBUF + (srow + 32 * i) * LDT + sc8] = B_[i]; } } while (0)
; template <int NK>
; DI void gemm_run(PF& pf, const u16* __restrict__ Ap, int lda, const u16* __restrict__ Wt, f32x16 (&acc)[2][2], char* smem) {
;     ...
;   __builtin_amdgcn_s_setprio(0);
;   __syncthreads();
;   BSTORE(pf.a0, pf.b0, 0);
;   BLOAD(pf.a0, pf.b0, 2);
;   __syncthreads();
; #pragma unroll
;   for (int kt = 0; kt < nk; kt += 2) {
;     BCOMP(0);
;     BSTORE(pf.a1, pf.b1, 1);
;     if (kt + 3 < nk) BLOAD(pf.a1, pf.b1, kt + 3);
;     __syncthreads();
;     BCOMP(1);
;     if (kt + 2 < nk) { BSTORE(pf.a0, pf.b0, 0); if (kt + 4 < nk) BLOAD(pf.a0, pf.b0, kt + 4); }
;     __syncthreads();
;   }
; DI void zero_acc(f32x16 (&acc)[2][2]) {
; #pragma unroll
;   for (int a = 0; a < 2; ++a)
; #pragma unroll
;     for (int b = 0; b < 2; ++b)
; #pragma unroll
;       for (int r = 0; r < 16; ++r) acc[a][b][r] = 0.f;
; }
.Linp_dirk:
	s_mov_b32 s15, 1
	v_mov_b32_e32 v2, 0
	v_mov_b32_e32 v3, 0
	v_mov_b32_e32 v4, 0
	v_mov_b32_e32 v5, 0
	v_mov_b32_e32 v6, 0
	v_mov_b32_e32 v7, 0
	v_mov_b32_e32 v8, 0
	v_mov_b32_e32 v9, 0
	v_mov_b32_e32 v10, 0
	v_mov_b32_e32 v11, 0
	v_mov_b32_e32 v12, 0
	v_mov_b32_e32 v13, 0
	v_mov_b32_e32 v14, 0
	v_mov_b32_e32 v15, 0
	v_mov_b32_e32 v16, 0
	v_mov_b32_e32 v17, 0
	v_mov_b32_e32 v18, 0
	v_mov_b32_e32 v19, 0
	v_mov_b32_e32 v20, 0
	v_mov_b32_e32 v21, 0
	v_mov_b32_e32 v22, 0
	v_mov_b32_e32 v23, 0
	v_mov_b32_e32 v24, 0
	v_mov_b32_e32 v25, 0
	v_mov_b32_e32 v26, 0
	v_mov_b32_e32 v27, 0
	v_mov_b32_e32 v28, 0
	v_mov_b32_e32 v29, 0
	v_mov_b32_e32 v30, 0
	v_mov_b32_e32 v31, 0
	v_mov_b32_e32 v32, 0
	v_mov_b32_e32 v33, 0
	v_mov_b32_e32 v34, 0
	v_mov_b32_e32 v35, 0
	v_mov_b32_e32 v36, 0
	v_mov_b32_e32 v37, 0
	v_mov_b32_e32 v38, 0
	v_mov_b32_e32 v39, 0
	v_mov_b32_e32 v40, 0
	v_mov_b32_e32 v41, 0
	v_mov_b32_e32 v42, 0
	v_mov_b32_e32 v43, 0
	v_mov_b32_e32 v44, 0
	v_mov_b32_e32 v45, 0
	v_mov_b32_e32 v46, 0
	v_mov_b32_e32 v47, 0
	v_mov_b32_e32 v48, 0
	v_mov_b32_e32 v49, 0
	v_mov_b32_e32 v50, 0
	v_mov_b32_e32 v51, 0
	v_mov_b32_e32 v52, 0
	v_mov_b32_e32 v53, 0
	v_mov_b32_e32 v54, 0
	v_mov_b32_e32 v55, 0
	v_mov_b32_e32 v56, 0
	v_mov_b32_e32 v57, 0
	v_mov_b32_e32 v58, 0
	v_mov_b32_e32 v59, 0
	v_mov_b32_e32 v60, 0
	v_mov_b32_e32 v61, 0
	v_mov_b32_e32 v62, 0
	v_mov_b32_e32 v63, 0
	v_mov_b32_e32 v64, 0
	v_mov_b32_e32 v65, 0
	v_mov_b32_e32 v74, 0
	v_mov_b32_e32 v75, 0
	v_mov_b32_e32 v76, 0
	v_mov_b32_e32 v77, 0
	v_mov_b32_e32 v78, 0
	v_mov_b32_e32 v79, 0
	v_mov_b32_e32 v80, 0
	v_mov_b32_e32 v81, 0
	v_mov_b32_e32 v82, 0
	v_mov_b32_e32 v83, 0
	v_mov_b32_e32 v84, 0
	v_mov_b32_e32 v85, 0
	v_mov_b32_e32 v86, 0
	v_mov_b32_e32 v87, 0
	v_mov_b32_e32 v88, 0
	v_mov_b32_e32 v89, 0
	v_mov_b32_e32 v90, 0
	v_mov_b32_e32 v91, 0
	v_mov_b32_e32 v92, 0
	v_mov_b32_e32 v93, 0
	v_mov_b32_e32 v94, 0
	v_mov_b32_e32 v95, 0
	v_mov_b32_e32 v96, 0
	v_mov_b32_e32 v97, 0
	v_mov_b32_e32 v98, 0
	v_mov_b32_e32 v99, 0
	v_mov_b32_e32 v100, 0
	v_mov_b32_e32 v101, 0
	v_mov_b32_e32 v102, 0
	v_mov_b32_e32 v103, 0
	v_mov_b32_e32 v104, 0
	v_mov_b32_e32 v105, 0
	v_mov_b32_e32 v106, 0
	v_mov_b32_e32 v107, 0
	v_mov_b32_e32 v108, 0
	v_mov_b32_e32 v109, 0
	v_mov_b32_e32 v110, 0
	v_mov_b32_e32 v111, 0
	v_mov_b32_e32 v112, 0
	v_mov_b32_e32 v113, 0
	v_mov_b32_e32 v114, 0
	v_mov_b32_e32 v115, 0
	v_mov_b32_e32 v116, 0
	v_mov_b32_e32 v117, 0
	v_mov_b32_e32 v118, 0
	v_mov_b32_e32 v119, 0
	v_mov_b32_e32 v120, 0
	v_mov_b32_e32 v121, 0
	v_mov_b32_e32 v208, 0
	v_mov_b32_e32 v209, 0
	v_mov_b32_e32 v210, 0
	v_mov_b32_e32 v211, 0
	v_mov_b32_e32 v212, 0
	v_mov_b32_e32 v213, 0
	v_mov_b32_e32 v214, 0
	v_mov_b32_e32 v215, 0
	v_mov_b32_e32 v216, 0
	v_mov_b32_e32 v217, 0
	v_mov_b32_e32 v218, 0
	v_mov_b32_e32 v219, 0
	v_mov_b32_e32 v220, 0
	v_mov_b32_e32 v221, 0
	v_mov_b32_e32 v222, 0
	v_mov_b32_e32 v223, 0
	s_add_u32 m0, s46, 0x0
	s_nop 0
	global_load_lds_dwordx4 v138, s[48:49]
	global_load_lds_dwordx4 v139, s[48:49] offset:1024
	s_add_u32 m0, s47, 0x0
	s_nop 0
	global_load_lds_dwordx4 v140, s[50:51]
	global_load_lds_dwordx4 v141, s[50:51] offset:1024
	global_load_lds_dwordx4 v142, s[50:51] offset:2048
	global_load_lds_dwordx4 v143, s[50:51] offset:3072
	s_add_u32 m0, s46, 0x6000
	s_add_u32 s48, s48, 0x100000
	s_addc_u32 s49, s49, 0
	global_load_lds_dwordx4 v138, s[48:49]
	global_load_lds_dwordx4 v139, s[48:49] offset:1024
	s_add_u32 m0, s47, 0x6000
	s_add_u32 s50, s50, s13
	s_addc_u32 s51, s51, 0
	global_load_lds_dwordx4 v140, s[50:51]
	global_load_lds_dwordx4 v141, s[50:51] offset:1024
	global_load_lds_dwordx4 v142, s[50:51] offset:2048
	global_load_lds_dwordx4 v143, s[50:51] offset:3072
	s_mov_b32 s12, 10
.Linpd_kloop:
	s_waitcnt vmcnt(6)
	s_barrier
	ds_read_b128 v[224:227], v126 offset:0
	ds_read_b128 v[240:243], v128 offset:0
	ds_read_b128 v[244:247], v128 offset:1024
	ds_read_b128 v[248:251], v128 offset:2048
	ds_read_b128 v[156:159], v128 offset:3072
	s_add_u32 m0, s46, 0xc000
	s_add_u32 s48, s48, 0x100000
	s_addc_u32 s49, s49, 0
	global_load_lds_dwordx4 v138, s[48:49]
	global_load_lds_dwordx4 v139, s[48:49] offset:1024
	s_add_u32 m0, s47, 0xc000
	s_add_u32 s50, s50, s13
	s_addc_u32 s51, s51, 0
	global_load_lds_dwordx4 v140, s[50:51]
	global_load_lds_dwordx4 v141, s[50:51] offset:1024
	global_load_lds_dwordx4 v142, s[50:51] offset:2048
	global_load_lds_dwordx4 v143, s[50:51] offset:3072
	ds_read_b128 v[228:231], v126 offset:1024
	ds_read_b128 v[232:235], v126 offset:2048
	ds_read_b128 v[236:239], v126 offset:3072
	ds_read_b128 v[160:163], v128 offset:8192
	ds_read_b128 v[164:167], v128 offset:9216
	ds_read_b128 v[168:171], v128 offset:10240
	ds_read_b128 v[122:125], v128 offset:11264
	s_waitcnt lgkmcnt(10)
	v_mfma_f32_16x16x32_bf16 v[2:5], v[240:243], v[224:227], v[2:5]
	s_waitcnt lgkmcnt(9)
	v_mfma_f32_16x16x32_bf16 v[6:9], v[244:247], v[224:227], v[6:9]
	s_waitcnt lgkmcnt(8)
	v_mfma_f32_16x16x32_bf16 v[10:13], v[248:251], v[224:227], v[10:13]
	s_waitcnt lgkmcnt(7)
	v_mfma_f32_16x16x32_bf16 v[14:17], v[156:159], v[224:227], v[14:17]
	s_waitcnt lgkmcnt(6)
	v_mfma_f32_16x16x32_bf16 v[18:21], v[240:243], v[228:231], v[18:21]
	v_mfma_f32_16x16x32_bf16 v[22:25], v[244:247], v[228:231], v[22:25]
	v_mfma_f32_16x16x32_bf16 v[26:29], v[248:251], v[228:231], v[26:29]
	v_mfma_f32_16x16x32_bf16 v[30:33], v[156:159], v[228:231], v[30:33]
	s_waitcnt lgkmcnt(5)
	v_mfma_f32_16x16x32_bf16 v[34:37], v[240:243], v[232:235], v[34:37]
	v_mfma_f32_16x16x32_bf16 v[38:41], v[244:247], v[232:235], v[38:41]
	v_mfma_f32_16x16x32_bf16 v[42:45], v[248:251], v[232:235], v[42:45]
	v_mfma_f32_16x16x32_bf16 v[46:49], v[156:159], v[232:235], v[46:49]
	s_waitcnt lgkmcnt(4)
; #define BLOAD(A_, B_, kt) do { _Pragma("unroll") for (int i = 0; i < 4; ++i) { \
;     A_[i] = *(const u32x4*)((const char*)Ap + (aoff + (unsigned)(32 * i * lda + (kt) * 64) * 2u)); B_[i] = *(const u32x4*)((const char*)Wt + (woff + (unsigned)(32 * i * K + (kt) * 64) * 2u)); } } while (0)
; #define BLOAD(A_, B_, kt) do { _Pragma("unroll") for (int i = 0; i < 4; ++i) { \
;     A_[i] = *(const u32x4*)((const char*)Ap + (aoff + (unsigned)(32 * i * lda + (kt) * 64) * 2u)); B_[i] = *(const u32x4*)((const char*)Wt + (woff + (unsigned)(32 * i * K + (kt) * 64) * 2u)); } } while (0)
; #define BSTORE(A_, B_, buf) do { _Pragma("unroll") for (int i = 0; i < 4; ++i) { \
;     *(u32x4*)&As[(buf) * GBUF + (srow + 32 * i) * LDT + sc8] = A_[i]; \
;     *(u32x4*)&Bs[(buf) * GBUF + (srow + 32 * i) * LDT + sc8] = B_[i]; } } while (0)
; template <int NK>
; DI void gemm_run(PF& pf, const u16* __restrict__ Ap, int lda, const u16* __restrict__ Wt, f32x16 (&acc)[2][2], char* smem) {
;     ...
; #pragma unroll
;   for (int kt = 0; kt < nk; kt += 2) {
;     BCOMP(0);
;     BSTORE(pf.a1, pf.b1, 1);
;     if (kt + 3 < nk) BLOAD(pf.a1, pf.b1, kt + 3);
;     __syncthreads();
;     BCOMP(1);
;     if (kt + 2 < nk) { BSTORE(pf.a0, pf.b0, 0); if (kt + 4 < nk) BLOAD(pf.a0, pf.b0, kt + 4); }
;     __syncthreads();
;   }
	v_mfma_f32_16x16x32_bf16 v[50:53], v[240:243], v[236:239], v[50:53]
	v_mfma_f32_16x16x32_bf16 v[54:57], v[244:247], v[236:239], v[54:57]
	v_mfma_f32_16x16x32_bf16 v[58:61], v[248:251], v[236:239], v[58:61]
	v_mfma_f32_16x16x32_bf16 v[62:65], v[156:159], v[236:239], v[62:65]
	s_waitcnt lgkmcnt(3)
	v_mfma_f32_16x16x32_bf16 v[74:77], v[160:163], v[224:227], v[74:77]
	s_waitcnt lgkmcnt(2)
	v_mfma_f32_16x16x32_bf16 v[78:81], v[164:167], v[224:227], v[78:81]
	s_waitcnt lgkmcnt(1)
	v_mfma_f32_16x16x32_bf16 v[82:85], v[168:171], v[224:227], v[82:85]
	s_waitcnt lgkmcnt(0)
	v_mfma_f32_16x16x32_bf16 v[86:89], v[122:125], v[224:227], v[86:89]
	v_mfma_f32_16x16x32_bf16 v[90:93], v[160:163], v[228:231], v[90:93]
	v_mfma_f32_16x16x32_bf16 v[94:97], v[164:167], v[228:231], v[94:97]
	v_mfma_f32_16x16x32_bf16 v[98:101], v[168:171], v[228:231], v[98:101]
	v_mfma_f32_16x16x32_bf16 v[102:105], v[122:125], v[228:231], v[102:105]
	v_mfma_f32_16x16x32_bf16 v[106:109], v[160:163], v[232:235], v[106:109]
	v_mfma_f32_16x16x32_bf16 v[110:113], v[164:167], v[232:235], v[110:113]
	v_mfma_f32_16x16x32_bf16 v[114:117], v[168:171], v[232:235], v[114:117]
	v_mfma_f32_16x16x32_bf16 v[118:121], v[122:125], v[232:235], v[118:121]
	v_mfma_f32_16x16x32_bf16 v[208:211], v[160:163], v[236:239], v[208:211]
	v_mfma_f32_16x16x32_bf16 v[212:215], v[164:167], v[236:239], v[212:215]
	v_mfma_f32_16x16x32_bf16 v[216:219], v[168:171], v[236:239], v[216:219]
	v_mfma_f32_16x16x32_bf16 v[220:223], v[122:125], v[236:239], v[220:223]
	s_waitcnt vmcnt(6)
	s_barrier
	ds_read_b128 v[224:227], v126 offset:24576
	ds_read_b128 v[240:243], v128 offset:24576
	ds_read_b128 v[244:247], v128 offset:25600
	ds_read_b128 v[248:251], v128 offset:26624
	ds_read_b128 v[156:159], v128 offset:27648
	s_add_u32 m0, s46, 0x0
	s_add_u32 s48, s48, 0x100000
	s_addc_u32 s49, s49, 0
	global_load_lds_dwordx4 v138, s[48:49]
	global_load_lds_dwordx4 v139, s[48:49] offset:1024
	s_add_u32 m0, s47, 0x0
	s_add_u32 s50, s50, s13
	s_addc_u32 s51, s51, 0
	global_load_lds_dwordx4 v140, s[50:51]
	global_load_lds_dwordx4 v141, s[50:51] offset:1024
	global_load_lds_dwordx4 v142, s[50:51] offset:2048
	global_load_lds_dwordx4 v143, s[50:51] offset:3072
	ds_read_b128 v[228:231], v126 offset:25600
	ds_read_b128 v[232:235], v126 offset:26624
	ds_read_b128 v[236:239], v126 offset:27648
	ds_read_b128 v[160:163], v128 offset:32768
	ds_read_b128 v[164:167], v128 offset:33792
	ds_read_b128 v[168:171], v128 offset:34816
	ds_read_b128 v[122:125], v128 offset:35840
	s_waitcnt lgkmcnt(10)
	v_mfma_f32_16x16x32_bf16 v[2:5], v[240:243], v[224:227], v[2:5]
	s_waitcnt lgkmcnt(9)
	v_mfma_f32_16x16x32_bf16 v[6:9], v[244:247], v[224:227], v[6:9]
	s_waitcnt lgkmcnt(8)
	v_mfma_f32_16x16x32_bf16 v[10:13], v[248:251], v[224:227], v[10:13]
	s_waitcnt lgkmcnt(7)
	v_mfma_f32_16x16x32_bf16 v[14:17], v[156:159], v[224:227], v[14:17]
	s_waitcnt lgkmcnt(6)
	v_mfma_f32_16x16x32_bf16 v[18:21], v[240:243], v[228:231], v[18:21]
	v_mfma_f32_16x16x32_bf16 v[22:25], v[244:247], v[228:231], v[22:25]
	v_mfma_f32_16x16x32_bf16 v[26:29], v[248:251], v[228:231], v[26:29]
	v_mfma_f32_16x16x32_bf16 v[30:33], v[156:159], v[228:231], v[30:33]
	s_waitcnt lgkmcnt(5)
	v_mfma_f32_16x16x32_bf16 v[34:37], v[240:243], v[232:235], v[34:37]
	v_mfma_f32_16x16x32_bf16 v[38:41], v[244:247], v[232:235], v[38:41]
	v_mfma_f32_16x16x32_bf16 v[42:45], v[248:251], v[232:235], v[42:45]
	v_mfma_f32_16x16x32_bf16 v[46:49], v[156:159], v[232:235], v[46:49]
	s_waitcnt lgkmcnt(4)
	v_mfma_f32_16x16x32_bf16 v[50:53], v[240:243], v[236:239], v[50:53]
	v_mfma_f32_16x16x32_bf16 v[54:57], v[244:247], v[236:239], v[54:57]
	v_mfma_f32_16x16x32_bf16 v[58:61], v[248:251], v[236:239], v[58:61]
	v_mfma_f32_16x16x32_bf16 v[62:65], v[156:159], v[236:239], v[62:65]
	s_waitcnt lgkmcnt(3)
	v_mfma_f32_16x16x32_bf16 v[74:77], v[160:163], v[224:227], v[74:77]
	s_waitcnt lgkmcnt(2)
	v_mfma_f32_16x16x32_bf16 v[78:81], v[164:167], v[224:227], v[78:81]
	s_waitcnt lgkmcnt(1)
	v_mfma_f32_16x16x32_bf16 v[82:85], v[168:171], v[224:227], v[82:85]
	s_waitcnt lgkmcnt(0)
	v_mfma_f32_16x16x32_bf16 v[86:89], v[122:125], v[224:227], v[86:89]
	v_mfma_f32_16x16x32_bf16 v[90:93], v[160:163], v[228:231], v[90:93]
	v_mfma_f32_16x16x32_bf16 v[94:97], v[164:167], v[228:231], v[94:97]
	v_mfma_f32_16x16x32_bf16 v[98:101], v[168:171], v[228:231], v[98:101]
	v_mfma_f32_16x16x32_bf16 v[102:105], v[122:125], v[228:231], v[102:105]
	v_mfma_f32_16x16x32_bf16 v[106:109], v[160:163], v[232:235], v[106:109]
	v_mfma_f32_16x16x32_bf16 v[110:113], v[164:167], v[232:235], v[110:113]
	v_mfma_f32_16x16x32_bf16 v[114:117], v[168:171], v[232:235], v[114:117]
	v_mfma_f32_16x16x32_bf16 v[118:121], v[122:125], v[232:235], v[118:121]
	v_mfma_f32_16x16x32_bf16 v[208:211], v[160:163], v[236:239], v[208:211]
	v_mfma_f32_16x16x32_bf16 v[212:215], v[164:167], v[236:239], v[212:215]
	v_mfma_f32_16x16x32_bf16 v[216:219], v[168:171], v[236:239], v[216:219]
	v_mfma_f32_16x16x32_bf16 v[220:223], v[122:125], v[236:239], v[220:223]
	s_waitcnt vmcnt(6)
	s_barrier
; #define BLOAD(A_, B_, kt) do { _Pragma("unroll") for (int i = 0; i < 4; ++i) { \
;     A_[i] = *(const u32x4*)((const char*)Ap + (aoff + (unsigned)(32 * i * lda + (kt) * 64) * 2u)); B_[i] = *(const u32x4*)((const char*)Wt + (woff + (unsigned)(32 * i * K + (kt) * 64) * 2u)); } } while (0)
; #define BLOAD(A_, B_, kt) do { _Pragma("unroll") for (int i = 0; i < 4; ++i) { \
;     A_[i] = *(const u32x4*)((const char*)Ap + (aoff + (unsigned)(32 * i * lda + (kt) * 64) * 2u)); B_[i] = *(const u32x4*)((const char*)Wt + (woff + (unsigned)(32 * i * K + (kt) * 64) * 2u)); } } while (0)
; #define BSTORE(A_, B_, buf) do { _Pragma("unroll") for (int i = 0; i < 4; ++i) { \
;     *(u32x4*)&As[(buf) * GBUF + (srow + 32 * i) * LDT + sc8] = A_[i]; \
;     *(u32x4*)&Bs[(buf) * GBUF + (srow + 32 * i) * LDT + sc8] = B_[i]; } } while (0)
; template <int NK>
; DI void gemm_run(PF& pf, const u16* __restrict__ Ap, int lda, const u16* __restrict__ Wt, f32x16 (&acc)[2][2], char* smem) {
;     ...
; #pragma unroll
;   for (int kt = 0; kt < nk; kt += 2) {
;     BCOMP(0);
;     BSTORE(pf.a1, pf.b1, 1);
;     if (kt + 3 < nk) BLOAD(pf.a1, pf.b1, kt + 3);
;     __syncthreads();
;     BCOMP(1);
;     if (kt + 2 < nk) { BSTORE(pf.a0, pf.b0, 0); if (kt + 4 < nk) BLOAD(pf.a0, pf.b0, kt + 4); }
;     __syncthreads();
;   }
	ds_read_b128 v[224:227], v126 offset:49152
	ds_read_b128 v[240:243], v128 offset:49152
	ds_read_b128 v[244:247], v128 offset:50176
	ds_read_b128 v[248:251], v128 offset:51200
	ds_read_b128 v[156:159], v128 offset:52224
	s_add_u32 m0, s46, 0x6000
	s_add_u32 s48, s48, 0x100000
	s_addc_u32 s49, s49, 0
	global_load_lds_dwordx4 v138, s[48:49]
	global_load_lds_dwordx4 v139, s[48:49] offset:1024
	s_add_u32 m0, s47, 0x6000
	s_add_u32 s50, s50, s13
	s_addc_u32 s51, s51, 0
	global_load_lds_dwordx4 v140, s[50:51]
	global_load_lds_dwordx4 v141, s[50:51] offset:1024
	global_load_lds_dwordx4 v142, s[50:51] offset:2048
	global_load_lds_dwordx4 v143, s[50:51] offset:3072
	ds_read_b128 v[228:231], v126 offset:50176
	ds_read_b128 v[232:235], v126 offset:51200
	ds_read_b128 v[236:239], v126 offset:52224
	ds_read_b128 v[160:163], v128 offset:57344
	ds_read_b128 v[164:167], v128 offset:58368
	ds_read_b128 v[168:171], v128 offset:59392
	ds_read_b128 v[122:125], v128 offset:60416
	s_waitcnt lgkmcnt(10)
	v_mfma_f32_16x16x32_bf16 v[2:5], v[240:243], v[224:227], v[2:5]
	s_waitcnt lgkmcnt(9)
	v_mfma_f32_16x16x32_bf16 v[6:9], v[244:247], v[224:227], v[6:9]
	s_waitcnt lgkmcnt(8)
	v_mfma_f32_16x16x32_bf16 v[10:13], v[248:251], v[224:227], v[10:13]
	s_waitcnt lgkmcnt(7)
	v_mfma_f32_16x16x32_bf16 v[14:17], v[156:159], v[224:227], v[14:17]
	s_waitcnt lgkmcnt(6)
	v_mfma_f32_16x16x32_bf16 v[18:21], v[240:243], v[228:231], v[18:21]
	v_mfma_f32_16x16x32_bf16 v[22:25], v[244:247], v[228:231], v[22:25]
	v_mfma_f32_16x16x32_bf16 v[26:29], v[248:251], v[228:231], v[26:29]
	v_mfma_f32_16x16x32_bf16 v[30:33], v[156:159], v[228:231], v[30:33]
	s_waitcnt lgkmcnt(5)
	v_mfma_f32_16x16x32_bf16 v[34:37], v[240:243], v[232:235], v[34:37]
	v_mfma_f32_16x16x32_bf16 v[38:41], v[244:247], v[232:235], v[38:41]
	v_mfma_f32_16x16x32_bf16 v[42:45], v[248:251], v[232:235], v[42:45]
	v_mfma_f32_16x16x32_bf16 v[46:49], v[156:159], v[232:235], v[46:49]
	s_waitcnt lgkmcnt(4)
	v_mfma_f32_16x16x32_bf16 v[50:53], v[240:243], v[236:239], v[50:53]
	v_mfma_f32_16x16x32_bf16 v[54:57], v[244:247], v[236:239], v[54:57]
	v_mfma_f32_16x16x32_bf16 v[58:61], v[248:251], v[236:239], v[58:61]
	v_mfma_f32_16x16x32_bf16 v[62:65], v[156:159], v[236:239], v[62:65]
	s_waitcnt lgkmcnt(3)
	v_mfma_f32_16x16x32_bf16 v[74:77], v[160:163], v[224:227], v[74:77]
	s_waitcnt lgkmcnt(2)
	v_mfma_f32_16x16x32_bf16 v[78:81], v[164:167], v[224:227], v[78:81]
	s_waitcnt lgkmcnt(1)
	v_mfma_f32_16x16x32_bf16 v[82:85], v[168:171], v[224:227], v[82:85]
	s_waitcnt lgkmcnt(0)
	v_mfma_f32_16x16x32_bf16 v[86:89], v[122:125], v[224:227], v[86:89]
	v_mfma_f32_16x16x32_bf16 v[90:93], v[160:163], v[228:231], v[90:93]
	v_mfma_f32_16x16x32_bf16 v[94:97], v[164:167], v[228:231], v[94:97]
	v_mfma_f32_16x16x32_bf16 v[98:101], v[168:171], v[228:231], v[98:101]
	v_mfma_f32_16x16x32_bf16 v[102:105], v[122:125], v[228:231], v[102:105]
	v_mfma_f32_16x16x32_bf16 v[106:109], v[160:163], v[232:235], v[106:109]
	v_mfma_f32_16x16x32_bf16 v[110:113], v[164:167], v[232:235], v[110:113]
	v_mfma_f32_16x16x32_bf16 v[114:117], v[168:171], v[232:235], v[114:117]
	v_mfma_f32_16x16x32_bf16 v[118:121], v[122:125], v[232:235], v[118:121]
	v_mfma_f32_16x16x32_bf16 v[208:211], v[160:163], v[236:239], v[208:211]
	v_mfma_f32_16x16x32_bf16 v[212:215], v[164:167], v[236:239], v[212:215]
	v_mfma_f32_16x16x32_bf16 v[216:219], v[168:171], v[236:239], v[216:219]
	v_mfma_f32_16x16x32_bf16 v[220:223], v[122:125], v[236:239], v[220:223]
	s_sub_u32 s12, s12, 1
	s_cmp_lg_u32 s12, 0
	s_cbranch_scc1 .Linpd_kloop
	s_waitcnt vmcnt(6)
	s_barrier
; #define BLOAD(A_, B_, kt) do { _Pragma("unroll") for (int i = 0; i < 4; ++i) { \
;     A_[i] = *(const u32x4*)((const char*)Ap + (aoff + (unsigned)(32 * i * lda + (kt) * 64) * 2u)); B_[i] = *(const u32x4*)((const char*)Wt + (woff + (unsigned)(32 * i * K + (kt) * 64) * 2u)); } } while (0)
; #define BLOAD(A_, B_, kt) do { _Pragma("unroll") for (int i = 0; i < 4; ++i) { \
;     A_[i] = *(const u32x4*)((const char*)Ap + (aoff + (unsigned)(32 * i * lda + (kt) * 64) * 2u)); B_[i] = *(const u32x4*)((const char*)Wt + (woff + (unsigned)(32 * i * K + (kt) * 64) * 2u)); } } while (0)
; #define BSTORE(A_, B_, buf) do { _Pragma("unroll") for (int i = 0; i < 4; ++i) { \
;     *(u32x4*)&As[(buf) * GBUF + (srow + 32 * i) * LDT + sc8] = A_[i]; \
;     *(u32x4*)&Bs[(buf) * GBUF + (srow + 32 * i) * LDT + sc8] = B_[i]; } } while (0)
; template <int NK>
; DI void gemm_run(PF& pf, const u16* __restrict__ Ap, int lda, const u16* __restrict__ Wt, f32x16 (&acc)[2][2], char* smem) {
;     ...
; #pragma unroll
;   for (int kt = 0; kt < nk; kt += 2) {
;     BCOMP(0);
;     BSTORE(pf.a1, pf.b1, 1);
;     if (kt + 3 < nk) BLOAD(pf.a1, pf.b1, kt + 3);
;     __syncthreads();
;     BCOMP(1);
;     if (kt + 2 < nk) { BSTORE(pf.a0, pf.b0, 0); if (kt + 4 < nk) BLOAD(pf.a0, pf.b0, kt + 4); }
;     __syncthreads();
;   }
	ds_read_b128 v[224:227], v126 offset:0
	ds_read_b128 v[240:243], v128 offset:0
	ds_read_b128 v[244:247], v128 offset:1024
	ds_read_b128 v[248:251], v128 offset:2048
	ds_read_b128 v[156:159], v128 offset:3072
	ds_read_b128 v[228:231], v126 offset:1024
	ds_read_b128 v[232:235], v126 offset:2048
	ds_read_b128 v[236:239], v126 offset:3072
	ds_read_b128 v[160:163], v128 offset:8192
	ds_read_b128 v[164:167], v128 offset:9216
	ds_read_b128 v[168:171], v128 offset:10240
	ds_read_b128 v[122:125], v128 offset:11264
	s_waitcnt lgkmcnt(10)
	v_mfma_f32_16x16x32_bf16 v[2:5], v[240:243], v[224:227], v[2:5]
	s_waitcnt lgkmcnt(9)
	v_mfma_f32_16x16x32_bf16 v[6:9], v[244:247], v[224:227], v[6:9]
	s_waitcnt lgkmcnt(8)
	v_mfma_f32_16x16x32_bf16 v[10:13], v[248:251], v[224:227], v[10:13]
	s_waitcnt lgkmcnt(7)
	v_mfma_f32_16x16x32_bf16 v[14:17], v[156:159], v[224:227], v[14:17]
	s_waitcnt lgkmcnt(6)
	v_mfma_f32_16x16x32_bf16 v[18:21], v[240:243], v[228:231], v[18:21]
	v_mfma_f32_16x16x32_bf16 v[22:25], v[244:247], v[228:231], v[22:25]
	v_mfma_f32_16x16x32_bf16 v[26:29], v[248:251], v[228:231], v[26:29]
	v_mfma_f32_16x16x32_bf16 v[30:33], v[156:159], v[228:231], v[30:33]
	s_waitcnt lgkmcnt(5)
	v_mfma_f32_16x16x32_bf16 v[34:37], v[240:243], v[232:235], v[34:37]
	v_mfma_f32_16x16x32_bf16 v[38:41], v[244:247], v[232:235], v[38:41]
	v_mfma_f32_16x16x32_bf16 v[42:45], v[248:251], v[232:235], v[42:45]
	v_mfma_f32_16x16x32_bf16 v[46:49], v[156:159], v[232:235], v[46:49]
	s_waitcnt lgkmcnt(4)
	v_mfma_f32_16x16x32_bf16 v[50:53], v[240:243], v[236:239], v[50:53]
	v_mfma_f32_16x16x32_bf16 v[54:57], v[244:247], v[236:239], v[54:57]
	v_mfma_f32_16x16x32_bf16 v[58:61], v[248:251], v[236:239], v[58:61]
	v_mfma_f32_16x16x32_bf16 v[62:65], v[156:159], v[236:239], v[62:65]
	s_waitcnt lgkmcnt(3)
	v_mfma_f32_16x16x32_bf16 v[74:77], v[160:163], v[224:227], v[74:77]
	s_waitcnt lgkmcnt(2)
	v_mfma_f32_16x16x32_bf16 v[78:81], v[164:167], v[224:227], v[78:81]
	s_waitcnt lgkmcnt(1)
	v_mfma_f32_16x16x32_bf16 v[82:85], v[168:171], v[224:227], v[82:85]
	s_waitcnt lgkmcnt(0)
	v_mfma_f32_16x16x32_bf16 v[86:89], v[122:125], v[224:227], v[86:89]
	v_mfma_f32_16x16x32_bf16 v[90:93], v[160:163], v[228:231], v[90:93]
	v_mfma_f32_16x16x32_bf16 v[94:97], v[164:167], v[228:231], v[94:97]
	v_mfma_f32_16x16x32_bf16 v[98:101], v[168:171], v[228:231], v[98:101]
	v_mfma_f32_16x16x32_bf16 v[102:105], v[122:125], v[228:231], v[102:105]
	v_mfma_f32_16x16x32_bf16 v[106:109], v[160:163], v[232:235], v[106:109]
	v_mfma_f32_16x16x32_bf16 v[110:113], v[164:167], v[232:235], v[110:113]
	v_mfma_f32_16x16x32_bf16 v[114:117], v[168:171], v[232:235], v[114:117]
	v_mfma_f32_16x16x32_bf16 v[118:121], v[122:125], v[232:235], v[118:121]
	v_mfma_f32_16x16x32_bf16 v[208:211], v[160:163], v[236:239], v[208:211]
	v_mfma_f32_16x16x32_bf16 v[212:215], v[164:167], v[236:239], v[212:215]
	v_mfma_f32_16x16x32_bf16 v[216:219], v[168:171], v[236:239], v[216:219]
	v_mfma_f32_16x16x32_bf16 v[220:223], v[122:125], v[236:239], v[220:223]
	s_waitcnt vmcnt(0)
	s_barrier
	ds_read_b128 v[224:227], v126 offset:24576
	ds_read_b128 v[240:243], v128 offset:24576
	ds_read_b128 v[244:247], v128 offset:25600
	ds_read_b128 v[248:251], v128 offset:26624
	ds_read_b128 v[156:159], v128 offset:27648
	ds_read_b128 v[228:231], v126 offset:25600
	ds_read_b128 v[232:235], v126 offset:26624
	ds_read_b128 v[236:239], v126 offset:27648
	ds_read_b128 v[160:163], v128 offset:32768
	ds_read_b128 v[164:167], v128 offset:33792
	ds_read_b128 v[168:171], v128 offset:34816
	ds_read_b128 v[122:125], v128 offset:35840
	s_waitcnt lgkmcnt(10)
	v_mfma_f32_16x16x32_bf16 v[2:5], v[240:243], v[224:227], v[2:5]
	s_waitcnt lgkmcnt(9)
	v_mfma_f32_16x16x32_bf16 v[6:9], v[244:247], v[224:227], v[6:9]
	s_waitcnt lgkmcnt(8)
	v_mfma_f32_16x16x32_bf16 v[10:13], v[248:251], v[224:227], v[10:13]
	s_waitcnt lgkmcnt(7)
	v_mfma_f32_16x16x32_bf16 v[14:17], v[156:159], v[224:227], v[14:17]
	s_waitcnt lgkmcnt(6)
	v_mfma_f32_16x16x32_bf16 v[18:21], v[240:243], v[228:231], v[18:21]
	v_mfma_f32_16x16x32_bf16 v[22:25], v[244:247], v[228:231], v[22:25]
	v_mfma_f32_16x16x32_bf16 v[26:29], v[248:251], v[228:231], v[26:29]
	v_mfma_f32_16x16x32_bf16 v[30:33], v[156:159], v[228:231], v[30:33]
	s_waitcnt lgkmcnt(5)
	v_mfma_f32_16x16x32_bf16 v[34:37], v[240:243], v[232:235], v[34:37]
	v_mfma_f32_16x16x32_bf16 v[38:41], v[244:247], v[232:235], v[38:41]
	v_mfma_f32_16x16x32_bf16 v[42:45], v[248:251], v[232:235], v[42:45]
	v_mfma_f32_16x16x32_bf16 v[46:49], v[156:159], v[232:235], v[46:49]
	s_waitcnt lgkmcnt(4)
	v_mfma_f32_16x16x32_bf16 v[50:53], v[240:243], v[236:239], v[50:53]
	v_mfma_f32_16x16x32_bf16 v[54:57], v[244:247], v[236:239], v[54:57]
	v_mfma_f32_16x16x32_bf16 v[58:61], v[248:251], v[236:239], v[58:61]
	v_mfma_f32_16x16x32_bf16 v[62:65], v[156:159], v[236:239], v[62:65]
	s_waitcnt lgkmcnt(3)
	v_mfma_f32_16x16x32_bf16 v[74:77], v[160:163], v[224:227], v[74:77]
	s_waitcnt lgkmcnt(2)
	v_mfma_f32_16x16x32_bf16 v[78:81], v[164:167], v[224:227], v[78:81]
	s_waitcnt lgkmcnt(1)
	v_mfma_f32_16x16x32_bf16 v[82:85], v[168:171], v[224:227], v[82:85]
	s_waitcnt lgkmcnt(0)
	v_mfma_f32_16x16x32_bf16 v[86:89], v[122:125], v[224:227], v[86:89]
	v_mfma_f32_16x16x32_bf16 v[90:93], v[160:163], v[228:231], v[90:93]
	v_mfma_f32_16x16x32_bf16 v[94:97], v[164:167], v[228:231], v[94:97]
	v_mfma_f32_16x16x32_bf16 v[98:101], v[168:171], v[228:231], v[98:101]
	v_mfma_f32_16x16x32_bf16 v[102:105], v[122:125], v[228:231], v[102:105]
	v_mfma_f32_16x16x32_bf16 v[106:109], v[160:163], v[232:235], v[106:109]
	v_mfma_f32_16x16x32_bf16 v[110:113], v[164:167], v[232:235], v[110:113]
	v_mfma_f32_16x16x32_bf16 v[114:117], v[168:171], v[232:235], v[114:117]
	v_mfma_f32_16x16x32_bf16 v[118:121], v[122:125], v[232:235], v[118:121]
	v_mfma_f32_16x16x32_bf16 v[208:211], v[160:163], v[236:239], v[208:211]
	v_mfma_f32_16x16x32_bf16 v[212:215], v[164:167], v[236:239], v[212:215]
	v_mfma_f32_16x16x32_bf16 v[216:219], v[168:171], v[236:239], v[216:219]
	v_mfma_f32_16x16x32_bf16 v[220:223], v[122:125], v[236:239], v[220:223]
	s_barrier
	s_branch .Linp_post

; DI void tile_inproj(const Params& p, int l, const Chunk& ck, int tile, int next, PF& pf, char* smem) {
;     ...
;   const int lt = m0 + row; const int S = ck.S; const int bl = lt >> ck.sshift, t = lt & (S - 1);
;   const float rinv = rinv_s[row];
;   float v[8];
;   if (ni < 24 || (ni >= 41 && ni < 45)) {
;     const float* gain; u16* dst; float scale;
;     if (ni < 24) {
;       const int g = (ni % 12) >> 2, h = ni & 3; const bool isq = ni < 12; const int dsh = 2 * g, d = 1 << dsh, Lg = S >> dsh;
;       gain = (const float*)(p.ws + OFF_GAINS) + (isq ? GN_DQ : GN_DK) + ((l * 3 + g) * 4 + h) * 128;
;       const int pp = (t & (d - 1)) * Lg + (t >> dsh);
;       dst = (u16*)(p.ws + (isq ? OFF_QD : OFF_KD)) + ((size_t)(g * CT + bl * S + pp)) * 512 + h * 128 + half * 64;
;       scale = isq ? QS128 : 1.f;
;     } else {
;       const int h = ni - 41; gain = (const float*)(p.ws + OFF_GAINS) + GN_MEMQ + l * 128;
;       dst = (u16*)(p.ws + OFF_MQ) + (size_t)lt * 512 + h * 128 + half * 64; scale = QS128;
;     }
;     float ssq = 0.f;
; #pragma unroll
;     for (int c8 = 0; c8 < 8; ++c8) { cs_ld8(Cs, row, half * 64 + c8 * 8, v);
; #pragma unroll
;       for (int j = 0; j < 8; ++j) ssq += v[j] * v[j]; }
;     ssq *= rinv * rinv; ssq += __shfl_xor(ssq, 1);
;     const float rn = rsqrtf(ssq * (1.f / 128.f) + EPS) * rinv * scale;
.LBB1_388:
	s_or_b64 exec, exec, s[34:35]
	s_cmp_lg_u32 s15, 0
	s_cbranch_scc0 .Linp_nodirect
	v_and_b32_e32 v130, 63, v172
	v_lshrrev_b32_e32 v131, 6, v172
	v_and_b32_e32 v132, 15, v130
	v_lshrrev_b32_e32 v133, 4, v130
	v_lshrrev_b32_e32 v134, 1, v131
	v_and_b32_e32 v135, 1, v131
	v_lshl_add_u32 v136, v134, 6, v132
	v_lshlrev_b32_e32 v137, 6, v135
	v_lshl_add_u32 v137, v133, 2, v137
	v_add_u32_e32 v148, s79, v136
	v_lshlrev_b32_e32 v149, 2, v136
	v_add_u32_e32 v149, 0x12000, v149
	v_lshl_add_u32 v150, v135, 7, v136
	v_lshlrev_b32_e32 v150, 2, v150
	v_xor_b32_e32 v151, 0x200, v150
	v_lshlrev_b32_e32 v152, 2, v137
	v_lshlrev_b32_e32 v153, 1, v137
	v_readfirstlane_b32 s57, v135
	s_waitcnt lgkmcnt(0)
	s_barrier
	ds_read_b32 v156, v149 offset:0
	ds_read_b32 v157, v149 offset:64
	ds_read_b32 v158, v149 offset:128
	ds_read_b32 v159, v149 offset:192
	s_waitcnt lgkmcnt(0)
	s_mov_b32 s12, s30
	s_cmp_lt_u32 s12, 24
	s_cbranch_scc1 .Linpd_dil_p0
	s_cmp_lt_u32 s12, 41
	s_cbranch_scc1 .Linpd_lat_p0
	s_cmp_lt_u32 s12, 45
	s_cbranch_scc1 .Linpd_mem_p0
	s_branch .Linpd_kr_p0
.Linpd_dil_p0:
	s_cmp_lt_u32 s12, 12
	s_cselect_b32 s0, 0, 12
	s_sub_i32 s0, s12, s0
	s_lshr_b32 s0, s0, 2
	s_lshl_b32 s40, s0, 1
	s_sub_i32 s41, s44, s40
	s_lshl_b32 s31, s0, 14
	v_readlane_b32 s13, v255, 28
	s_mul_i32 s13, s13, 3
	s_add_i32 s13, s13, s0
	s_lshl_b32 s13, s13, 2
	s_and_b32 s15, s12, 3
	s_add_i32 s13, s13, s15
	s_lshl_b32 s13, s13, 9
	s_lshl_b32 s15, s15, 8
	s_mov_b32 s36, 0x9b80000
	s_cmp_lt_u32 s12, 12
	s_cselect_b32 s56, 0x3e0293ee, 1.0
	s_cselect_b32 s36, 0x6b80000, s36
	s_cselect_b32 s0, 0, 0x3000
	s_add_u32 s34, s55, s0
	s_addc_u32 s35, s74, 0
	s_add_u32 s34, s34, s13
	s_addc_u32 s35, s35, 0
	s_add_u32 s36, s36, s15
	s_add_u32 s36, s18, s36
	s_addc_u32 s37, s19, 0
	v_mov_b32_e32 v240, v148
	v_lshrrev_b32_e32 v241, s44, v240
	v_and_b32_e32 v240, s54, v240
	v_lshlrev_b32_e32 v241, s44, v241
	v_bfe_u32 v242, v240, 0, s40
	v_lshrrev_b32_e32 v240, s40, v240
	v_lshlrev_b32_e32 v242, s41, v242
	v_add3_u32 v240, v240, v241, v242
	v_add_u32_e32 v240, s31, v240
	v_lshl_add_u32 v168, v240, 10, v153
	v_add_u32_e32 v240, 16, v148
	v_lshrrev_b32_e32 v241, s44, v240
	v_and_b32_e32 v240, s54, v240
	v_lshlrev_b32_e32 v241, s44, v241
	v_bfe_u32 v242, v240, 0, s40
	v_lshrrev_b32_e32 v240, s40, v240
	v_lshlrev_b32_e32 v242, s41, v242
	v_add3_u32 v240, v240, v241, v242
	v_add_u32_e32 v240, s31, v240
	v_lshl_add_u32 v169, v240, 10, v153
	v_add_u32_e32 v240, 32, v148
	v_lshrrev_b32_e32 v241, s44, v240
	v_and_b32_e32 v240, s54, v240
	v_lshlrev_b32_e32 v241, s44, v241
	v_bfe_u32 v242, v240, 0, s40
	v_lshrrev_b32_e32 v240, s40, v240
	v_lshlrev_b32_e32 v242, s41, v242
	v_add3_u32 v240, v240, v241, v242
	v_add_u32_e32 v240, s31, v240
	v_lshl_add_u32 v170, v240, 10, v153
	v_add_u32_e32 v240, 48, v148
	v_lshrrev_b32_e32 v241, s44, v240
	v_and_b32_e32 v240, s54, v240
	v_lshlrev_b32_e32 v241, s44, v241
	v_bfe_u32 v242, v240, 0, s40
	v_lshrrev_b32_e32 v240, s40, v240
	v_lshlrev_b32_e32 v242, s41, v242
	v_add3_u32 v240, v240, v241, v242
	v_add_u32_e32 v240, s31, v240
	v_lshl_add_u32 v171, v240, 10, v153
	s_branch .Linpd_norm_p0
.Linpd_mem_p0:
	s_mov_b64 s[34:35], s[26:27]
	s_sub_i32 s0, s12, 41
	s_lshl_b32 s0, s0, 8
	s_add_u32 s0, s0, 0x11080000
	s_add_u32 s36, s18, s0
	s_addc_u32 s37, s19, 0
	s_mov_b32 s56, 0x3e0293ee
	v_mov_b32_e32 v240, v148
	v_lshl_add_u32 v168, v240, 10, v153
	v_add_u32_e32 v240, 16, v148
	v_lshl_add_u32 v169, v240, 10, v153
	v_add_u32_e32 v240, 32, v148
	v_lshl_add_u32 v170, v240, 10, v153
	v_add_u32_e32 v240, 48, v148
	v_lshl_add_u32 v171, v240, 10, v153
.Linpd_norm_p0:
	global_load_dwordx4 v[224:227], v152, s[34:35] offset:0
	global_load_dwordx4 v[228:231], v152, s[34:35] offset:64
	global_load_dwordx4 v[232:235], v152, s[34:35] offset:128
	global_load_dwordx4 v[236:239], v152, s[34:35] offset:192
	v_mul_f32_e32 v160, v2, v2
	v_fmac_f32_e32 v160, v3, v3
	v_fmac_f32_e32 v160, v4, v4
	v_fmac_f32_e32 v160, v5, v5
	v_fmac_f32_e32 v160, v6, v6
	v_fmac_f32_e32 v160, v7, v7
	v_fmac_f32_e32 v160, v8, v8
	v_fmac_f32_e32 v160, v9, v9
	v_fmac_f32_e32 v160, v10, v10
	v_fmac_f32_e32 v160, v11, v11
	v_fmac_f32_e32 v160, v12, v12
	v_fmac_f32_e32 v160, v13, v13
	v_fmac_f32_e32 v160, v14, v14
	v_fmac_f32_e32 v160, v15, v15
	v_fmac_f32_e32 v160, v16, v16
	v_fmac_f32_e32 v160, v17, v17
	v_mul_f32_e32 v161, v18, v18
	v_fmac_f32_e32 v161, v19, v19
	v_fmac_f32_e32 v161, v20, v20
	v_fmac_f32_e32 v161, v21, v21
	v_fmac_f32_e32 v161, v22, v22
	v_fmac_f32_e32 v161, v23, v23
	v_fmac_f32_e32 v161, v24, v24
	v_fmac_f32_e32 v161, v25, v25
	v_fmac_f32_e32 v161, v26, v26
	v_fmac_f32_e32 v161, v27, v27
	v_fmac_f32_e32 v161, v28, v28
	v_fmac_f32_e32 v161, v29, v29
	v_fmac_f32_e32 v161, v30, v30
	v_fmac_f32_e32 v161, v31, v31
	v_fmac_f32_e32 v161, v32, v32
	v_fmac_f32_e32 v161, v33, v33
	v_mul_f32_e32 v162, v34, v34
	v_fmac_f32_e32 v162, v35, v35
	v_fmac_f32_e32 v162, v36, v36
	v_fmac_f32_e32 v162, v37, v37
	v_fmac_f32_e32 v162, v38, v38
	v_fmac_f32_e32 v162, v39, v39
	v_fmac_f32_e32 v162, v40, v40
	v_fmac_f32_e32 v162, v41, v41
	v_fmac_f32_e32 v162, v42, v42
	v_fmac_f32_e32 v162, v43, v43
	v_fmac_f32_e32 v162, v44, v44
	v_fmac_f32_e32 v162, v45, v45
	v_fmac_f32_e32 v162, v46, v46
	v_fmac_f32_e32 v162, v47, v47
	v_fmac_f32_e32 v162, v48, v48
	v_fmac_f32_e32 v162, v49, v49
	v_mul_f32_e32 v163, v50, v50
	v_fmac_f32_e32 v163, v51, v51
	v_fmac_f32_e32 v163, v52, v52
	v_fmac_f32_e32 v163, v53, v53
	v_fmac_f32_e32 v163, v54, v54
	v_fmac_f32_e32 v163, v55, v55
	v_fmac_f32_e32 v163, v56, v56
	v_fmac_f32_e32 v163, v57, v57
	v_fmac_f32_e32 v163, v58, v58
	v_fmac_f32_e32 v163, v59, v59
	v_fmac_f32_e32 v163, v60, v60
	v_fmac_f32_e32 v163, v61, v61
	v_fmac_f32_e32 v163, v62, v62
	v_fmac_f32_e32 v163, v63, v63
	v_fmac_f32_e32 v163, v64, v64
	v_fmac_f32_e32 v163, v65, v65
	ds_swizzle_b32 v240, v160 offset:0x401f
	ds_swizzle_b32 v241, v161 offset:0x401f
	ds_swizzle_b32 v242, v162 offset:0x401f
	ds_swizzle_b32 v243, v163 offset:0x401f
	s_waitcnt lgkmcnt(0)
	v_add_f32_e32 v160, v160, v240
	v_add_f32_e32 v161, v161, v241
	v_add_f32_e32 v162, v162, v242
	v_add_f32_e32 v163, v163, v243
	v_mov_b32_e32 v240, v160
	v_mov_b32_e32 v241, v161
	v_mov_b32_e32 v242, v162
	v_mov_b32_e32 v243, v163
	s_nop 1
	v_permlane32_swap_b32_e32 v160, v240
	v_permlane32_swap_b32_e32 v161, v241
	v_permlane32_swap_b32_e32 v162, v242
	v_permlane32_swap_b32_e32 v163, v243
	s_nop 1
	v_add_f32_e32 v160, v160, v240
	v_add_f32_e32 v161, v161, v241
	v_add_f32_e32 v162, v162, v242
	v_add_f32_e32 v163, v163, v243
	ds_write_b32 v150, v160 offset:0
	ds_write_b32 v150, v161 offset:64
	ds_write_b32 v150, v162 offset:128
	ds_write_b32 v150, v163 offset:192
	s_waitcnt lgkmcnt(0)
	s_barrier
; DI void st8(u16* dst, const float (&v)[8]) { *(u32x4*)dst = pack8(v); }
; DI void tile_inproj(const Params& p, int l, const Chunk& ck, int tile, int next, PF& pf, char* smem) {
;     ...
;     ssq *= rinv * rinv; ssq += __shfl_xor(ssq, 1);
;     const float rn = rsqrtf(ssq * (1.f / 128.f) + EPS) * rinv * scale;
; #pragma unroll
;     for (int c8 = 0; c8 < 8; ++c8) { cs_ld8(Cs, row, half * 64 + c8 * 8, v);
; #pragma unroll
;       for (int j = 0; j < 8; ++j) v[j] = v[j] * rn * gain[half * 64 + c8 * 8 + j];
;       st8(dst + c8 * 8, v); }
	ds_read_b32 v164, v151 offset:0
	ds_read_b32 v165, v151 offset:64
	ds_read_b32 v166, v151 offset:128
	ds_read_b32 v167, v151 offset:192
	s_waitcnt lgkmcnt(0)
	v_add_f32_e32 v160, v160, v164
	v_mul_f32_e32 v240, v156, v156
	v_add_f32_e32 v161, v161, v165
	v_mul_f32_e32 v241, v157, v157
	v_add_f32_e32 v162, v162, v166
	v_mul_f32_e32 v242, v158, v158
	v_add_f32_e32 v163, v163, v167
	v_mul_f32_e32 v243, v159, v159
	v_mul_f32_e32 v160, v160, v240
	v_fmamk_f32 v160, v160, 0x3c000000, v188
	v_mul_f32_e32 v161, v161, v241
	v_fmamk_f32 v161, v161, 0x3c000000, v188
	v_mul_f32_e32 v162, v162, v242
	v_fmamk_f32 v162, v162, 0x3c000000, v188
	v_mul_f32_e32 v163, v163, v243
	v_fmamk_f32 v163, v163, 0x3c000000, v188
	v_rsq_f32_e32 v160, v160
	v_rsq_f32_e32 v161, v161
	v_rsq_f32_e32 v162, v162
	v_rsq_f32_e32 v163, v163
	s_nop 0
	v_mul_f32_e32 v160, v160, v156
	v_mul_f32_e32 v160, s56, v160
	v_mul_f32_e32 v161, v161, v157
	v_mul_f32_e32 v161, s56, v161
	v_mul_f32_e32 v162, v162, v158
	v_mul_f32_e32 v162, s56, v162
	v_mul_f32_e32 v163, v163, v159
	v_mul_f32_e32 v163, s56, v163
	s_waitcnt vmcnt(0)
	v_mul_f32_e32 v2, v2, v160
	v_mul_f32_e32 v3, v3, v160
	v_mul_f32_e32 v4, v4, v160
	v_mul_f32_e32 v5, v5, v160
	v_mul_f32_e32 v2, v2, v224
	v_mul_f32_e32 v3, v3, v225
	v_mul_f32_e32 v4, v4, v226
	v_mul_f32_e32 v5, v5, v227
	v_cvt_pk_bf16_f32 v2, v2, v3
	v_cvt_pk_bf16_f32 v3, v4, v5
	global_store_dwordx2 v168, v[2:3], s[36:37]
	v_mul_f32_e32 v6, v6, v160
	v_mul_f32_e32 v7, v7, v160
	v_mul_f32_e32 v8, v8, v160
	v_mul_f32_e32 v9, v9, v160
	v_mul_f32_e32 v6, v6, v228
	v_mul_f32_e32 v7, v7, v229
	v_mul_f32_e32 v8, v8, v230
	v_mul_f32_e32 v9, v9, v231
	v_cvt_pk_bf16_f32 v6, v6, v7
	v_cvt_pk_bf16_f32 v7, v8, v9
	global_store_dwordx2 v168, v[6:7], s[36:37] offset:32
	v_mul_f32_e32 v10, v10, v160
	v_mul_f32_e32 v11, v11, v160
	v_mul_f32_e32 v12, v12, v160
	v_mul_f32_e32 v13, v13, v160
	v_mul_f32_e32 v10, v10, v232
	v_mul_f32_e32 v11, v11, v233
	v_mul_f32_e32 v12, v12, v234
	v_mul_f32_e32 v13, v13, v235
	v_cvt_pk_bf16_f32 v10, v10, v11
	v_cvt_pk_bf16_f32 v11, v12, v13
	global_store_dwordx2 v168, v[10:11], s[36:37] offset:64
	v_mul_f32_e32 v14, v14, v160
	v_mul_f32_e32 v15, v15, v160
	v_mul_f32_e32 v16, v16, v160
	v_mul_f32_e32 v17, v17, v160
	v_mul_f32_e32 v14, v14, v236
	v_mul_f32_e32 v15, v15, v237
	v_mul_f32_e32 v16, v16, v238
	v_mul_f32_e32 v17, v17, v239
	v_cvt_pk_bf16_f32 v14, v14, v15
	v_cvt_pk_bf16_f32 v15, v16, v17
	global_store_dwordx2 v168, v[14:15], s[36:37] offset:96
	v_mul_f32_e32 v18, v18, v161
	v_mul_f32_e32 v19, v19, v161
	v_mul_f32_e32 v20, v20, v161
	v_mul_f32_e32 v21, v21, v161
	v_mul_f32_e32 v18, v18, v224
	v_mul_f32_e32 v19, v19, v225
	v_mul_f32_e32 v20, v20, v226
	v_mul_f32_e32 v21, v21, v227
	v_cvt_pk_bf16_f32 v18, v18, v19
	v_cvt_pk_bf16_f32 v19, v20, v21
	global_store_dwordx2 v169, v[18:19], s[36:37]
	v_mul_f32_e32 v22, v22, v161
	v_mul_f32_e32 v23, v23, v161
	v_mul_f32_e32 v24, v24, v161
	v_mul_f32_e32 v25, v25, v161
	v_mul_f32_e32 v22, v22, v228
	v_mul_f32_e32 v23, v23, v229
	v_mul_f32_e32 v24, v24, v230
	v_mul_f32_e32 v25, v25, v231
	v_cvt_pk_bf16_f32 v22, v22, v23
	v_cvt_pk_bf16_f32 v23, v24, v25
	global_store_dwordx2 v169, v[22:23], s[36:37] offset:32
	v_mul_f32_e32 v26, v26, v161
	v_mul_f32_e32 v27, v27, v161
	v_mul_f32_e32 v28, v28, v161
	v_mul_f32_e32 v29, v29, v161
	v_mul_f32_e32 v26, v26, v232
	v_mul_f32_e32 v27, v27, v233
	v_mul_f32_e32 v28, v28, v234
	v_mul_f32_e32 v29, v29, v235
	v_cvt_pk_bf16_f32 v26, v26, v27
	v_cvt_pk_bf16_f32 v27, v28, v29
	global_store_dwordx2 v169, v[26:27], s[36:37] offset:64
	v_mul_f32_e32 v30, v30, v161
	v_mul_f32_e32 v31, v31, v161
	v_mul_f32_e32 v32, v32, v161
	v_mul_f32_e32 v33, v33, v161
	v_mul_f32_e32 v30, v30, v236
	v_mul_f32_e32 v31, v31, v237
	v_mul_f32_e32 v32, v32, v238
	v_mul_f32_e32 v33, v33, v239
	v_cvt_pk_bf16_f32 v30, v30, v31
	v_cvt_pk_bf16_f32 v31, v32, v33
	global_store_dwordx2 v169, v[30:31], s[36:37] offset:96
	v_mul_f32_e32 v34, v34, v162
	v_mul_f32_e32 v35, v35, v162
	v_mul_f32_e32 v36, v36, v162
	v_mul_f32_e32 v37, v37, v162
	v_mul_f32_e32 v34, v34, v224
	v_mul_f32_e32 v35, v35, v225
	v_mul_f32_e32 v36, v36, v226
	v_mul_f32_e32 v37, v37, v227
	v_cvt_pk_bf16_f32 v34, v34, v35
	v_cvt_pk_bf16_f32 v35, v36, v37
	global_store_dwordx2 v170, v[34:35], s[36:37]
	v_mul_f32_e32 v38, v38, v162
	v_mul_f32_e32 v39, v39, v162
	v_mul_f32_e32 v40, v40, v162
	v_mul_f32_e32 v41, v41, v162
	v_mul_f32_e32 v38, v38, v228
	v_mul_f32_e32 v39, v39, v229
	v_mul_f32_e32 v40, v40, v230
	v_mul_f32_e32 v41, v41, v231
	v_cvt_pk_bf16_f32 v38, v38, v39
	v_cvt_pk_bf16_f32 v39, v40, v41
	global_store_dwordx2 v170, v[38:39], s[36:37] offset:32
	v_mul_f32_e32 v42, v42, v162
	v_mul_f32_e32 v43, v43, v162
	v_mul_f32_e32 v44, v44, v162
	v_mul_f32_e32 v45, v45, v162
	v_mul_f32_e32 v42, v42, v232
	v_mul_f32_e32 v43, v43, v233
	v_mul_f32_e32 v44, v44, v234
	v_mul_f32_e32 v45, v45, v235
	v_cvt_pk_bf16_f32 v42, v42, v43
	v_cvt_pk_bf16_f32 v43, v44, v45
	global_store_dwordx2 v170, v[42:43], s[36:37] offset:64
	v_mul_f32_e32 v46, v46, v162
	v_mul_f32_e32 v47, v47, v162
	v_mul_f32_e32 v48, v48, v162
	v_mul_f32_e32 v49, v49, v162
	v_mul_f32_e32 v46, v46, v236
	v_mul_f32_e32 v47, v47, v237
	v_mul_f32_e32 v48, v48, v238
	v_mul_f32_e32 v49, v49, v239
	v_cvt_pk_bf16_f32 v46, v46, v47
	v_cvt_pk_bf16_f32 v47, v48, v49
	global_store_dwordx2 v170, v[46:47], s[36:37] offset:96
	v_mul_f32_e32 v50, v50, v163
	v_mul_f32_e32 v51, v51, v163
	v_mul_f32_e32 v52, v52, v163
	v_mul_f32_e32 v53, v53, v163
	v_mul_f32_e32 v50, v50, v224
	v_mul_f32_e32 v51, v51, v225
	v_mul_f32_e32 v52, v52, v226
	v_mul_f32_e32 v53, v53, v227
	v_cvt_pk_bf16_f32 v50, v50, v51
	v_cvt_pk_bf16_f32 v51, v52, v53
	global_store_dwordx2 v171, v[50:51], s[36:37]
	v_mul_f32_e32 v54, v54, v163
	v_mul_f32_e32 v55, v55, v163
	v_mul_f32_e32 v56, v56, v163
	v_mul_f32_e32 v57, v57, v163
	v_mul_f32_e32 v54, v54, v228
	v_mul_f32_e32 v55, v55, v229
	v_mul_f32_e32 v56, v56, v230
	v_mul_f32_e32 v57, v57, v231
	v_cvt_pk_bf16_f32 v54, v54, v55
	v_cvt_pk_bf16_f32 v55, v56, v57
	global_store_dwordx2 v171, v[54:55], s[36:37] offset:32
	v_mul_f32_e32 v58, v58, v163
	v_mul_f32_e32 v59, v59, v163
	v_mul_f32_e32 v60, v60, v163
	v_mul_f32_e32 v61, v61, v163
	v_mul_f32_e32 v58, v58, v232
	v_mul_f32_e32 v59, v59, v233
	v_mul_f32_e32 v60, v60, v234
	v_mul_f32_e32 v61, v61, v235
	v_cvt_pk_bf16_f32 v58, v58, v59
	v_cvt_pk_bf16_f32 v59, v60, v61
	global_store_dwordx2 v171, v[58:59], s[36:37] offset:64
	v_mul_f32_e32 v62, v62, v163
	v_mul_f32_e32 v63, v63, v163
	v_mul_f32_e32 v64, v64, v163
	v_mul_f32_e32 v65, v65, v163
	v_mul_f32_e32 v62, v62, v236
	v_mul_f32_e32 v63, v63, v237
	v_mul_f32_e32 v64, v64, v238
	v_mul_f32_e32 v65, v65, v239
	v_cvt_pk_bf16_f32 v62, v62, v63
	v_cvt_pk_bf16_f32 v63, v64, v65
	global_store_dwordx2 v171, v[62:63], s[36:37] offset:96
	s_branch .Linpd_done_p0
; DI void st8(u16* dst, const float (&v)[8]) { *(u32x4*)dst = pack8(v); }
; DI void tile_inproj(const Params& p, int l, const Chunk& ck, int tile, int next, PF& pf, char* smem) {
;     ...
;   } else if (ni < 41) {
;     u16* dst = (ni < 39) ? (u16*)(p.ws + OFF_CQ) + (size_t)lt * 384 + (ni - 36) * 128 + half * 64 : (u16*)(p.ws + OFF_CKV) + (size_t)lt * 256 + (ni - 39) * 128 + half * 64;
; #pragma unroll
;     for (int c8 = 0; c8 < 8; ++c8) { cs_ld8(Cs, row, half * 64 + c8 * 8, v);
; #pragma unroll
;       for (int j = 0; j < 8; ++j) v[j] *= rinv;
;       st8(dst + c8 * 8, v); }
.Linpd_lat_p0:
	s_cmp_lt_u32 s12, 39
	s_cbranch_scc0 .Linpd_ckv_p0
	s_sub_i32 s0, s12, 36
	s_lshl_b32 s0, s0, 8
	s_add_u32 s0, s0, 0xfb80000
	s_add_u32 s36, s18, s0
	s_addc_u32 s37, s19, 0
	v_mov_b32_e32 v240, v148
	v_mul_u32_u24_e32 v240, 0x300, v240
	v_add_u32_e32 v168, v240, v153
	v_add_u32_e32 v240, 16, v148
	v_mul_u32_u24_e32 v240, 0x300, v240
	v_add_u32_e32 v169, v240, v153
	v_add_u32_e32 v240, 32, v148
	v_mul_u32_u24_e32 v240, 0x300, v240
	v_add_u32_e32 v170, v240, v153
	v_add_u32_e32 v240, 48, v148
	v_mul_u32_u24_e32 v240, 0x300, v240
	v_add_u32_e32 v171, v240, v153
	s_branch .Linpd_plain_p0
.Linpd_ckv_p0:
	s_sub_i32 s0, s12, 39
	s_lshl_b32 s0, s0, 8
	s_add_u32 s0, s0, 0x10780000
	s_add_u32 s36, s18, s0
	s_addc_u32 s37, s19, 0
	v_mov_b32_e32 v240, v148
	v_lshl_add_u32 v168, v240, 9, v153
	v_add_u32_e32 v240, 16, v148
	v_lshl_add_u32 v169, v240, 9, v153
	v_add_u32_e32 v240, 32, v148
	v_lshl_add_u32 v170, v240, 9, v153
	v_add_u32_e32 v240, 48, v148
	v_lshl_add_u32 v171, v240, 9, v153
.Linpd_plain_p0:
	v_mul_f32_e32 v2, v2, v156
	v_mul_f32_e32 v3, v3, v156
	v_mul_f32_e32 v4, v4, v156
	v_mul_f32_e32 v5, v5, v156
	v_cvt_pk_bf16_f32 v2, v2, v3
	v_cvt_pk_bf16_f32 v3, v4, v5
	global_store_dwordx2 v168, v[2:3], s[36:37]
	v_mul_f32_e32 v6, v6, v156
	v_mul_f32_e32 v7, v7, v156
	v_mul_f32_e32 v8, v8, v156
	v_mul_f32_e32 v9, v9, v156
	v_cvt_pk_bf16_f32 v6, v6, v7
	v_cvt_pk_bf16_f32 v7, v8, v9
	global_store_dwordx2 v168, v[6:7], s[36:37] offset:32
	v_mul_f32_e32 v10, v10, v156
	v_mul_f32_e32 v11, v11, v156
	v_mul_f32_e32 v12, v12, v156
	v_mul_f32_e32 v13, v13, v156
	v_cvt_pk_bf16_f32 v10, v10, v11
	v_cvt_pk_bf16_f32 v11, v12, v13
	global_store_dwordx2 v168, v[10:11], s[36:37] offset:64
	v_mul_f32_e32 v14, v14, v156
	v_mul_f32_e32 v15, v15, v156
	v_mul_f32_e32 v16, v16, v156
	v_mul_f32_e32 v17, v17, v156
	v_cvt_pk_bf16_f32 v14, v14, v15
	v_cvt_pk_bf16_f32 v15, v16, v17
	global_store_dwordx2 v168, v[14:15], s[36:37] offset:96
	v_mul_f32_e32 v18, v18, v157
	v_mul_f32_e32 v19, v19, v157
	v_mul_f32_e32 v20, v20, v157
	v_mul_f32_e32 v21, v21, v157
	v_cvt_pk_bf16_f32 v18, v18, v19
	v_cvt_pk_bf16_f32 v19, v20, v21
	global_store_dwordx2 v169, v[18:19], s[36:37]
	v_mul_f32_e32 v22, v22, v157
	v_mul_f32_e32 v23, v23, v157
	v_mul_f32_e32 v24, v24, v157
	v_mul_f32_e32 v25, v25, v157
	v_cvt_pk_bf16_f32 v22, v22, v23
	v_cvt_pk_bf16_f32 v23, v24, v25
	global_store_dwordx2 v169, v[22:23], s[36:37] offset:32
	v_mul_f32_e32 v26, v26, v157
	v_mul_f32_e32 v27, v27, v157
	v_mul_f32_e32 v28, v28, v157
	v_mul_f32_e32 v29, v29, v157
	v_cvt_pk_bf16_f32 v26, v26, v27
	v_cvt_pk_bf16_f32 v27, v28, v29
	global_store_dwordx2 v169, v[26:27], s[36:37] offset:64
	v_mul_f32_e32 v30, v30, v157
	v_mul_f32_e32 v31, v31, v157
	v_mul_f32_e32 v32, v32, v157
	v_mul_f32_e32 v33, v33, v157
	v_cvt_pk_bf16_f32 v30, v30, v31
	v_cvt_pk_bf16_f32 v31, v32, v33
	global_store_dwordx2 v169, v[30:31], s[36:37] offset:96
	v_mul_f32_e32 v34, v34, v158
	v_mul_f32_e32 v35, v35, v158
	v_mul_f32_e32 v36, v36, v158
	v_mul_f32_e32 v37, v37, v158
	v_cvt_pk_bf16_f32 v34, v34, v35
	v_cvt_pk_bf16_f32 v35, v36, v37
	global_store_dwordx2 v170, v[34:35], s[36:37]
	v_mul_f32_e32 v38, v38, v158
	v_mul_f32_e32 v39, v39, v158
	v_mul_f32_e32 v40, v40, v158
	v_mul_f32_e32 v41, v41, v158
	v_cvt_pk_bf16_f32 v38, v38, v39
	v_cvt_pk_bf16_f32 v39, v40, v41
	global_store_dwordx2 v170, v[38:39], s[36:37] offset:32
	v_mul_f32_e32 v42, v42, v158
	v_mul_f32_e32 v43, v43, v158
	v_mul_f32_e32 v44, v44, v158
	v_mul_f32_e32 v45, v45, v158
	v_cvt_pk_bf16_f32 v42, v42, v43
	v_cvt_pk_bf16_f32 v43, v44, v45
	global_store_dwordx2 v170, v[42:43], s[36:37] offset:64
	v_mul_f32_e32 v46, v46, v158
	v_mul_f32_e32 v47, v47, v158
	v_mul_f32_e32 v48, v48, v158
	v_mul_f32_e32 v49, v49, v158
	v_cvt_pk_bf16_f32 v46, v46, v47
	v_cvt_pk_bf16_f32 v47, v48, v49
	global_store_dwordx2 v170, v[46:47], s[36:37] offset:96
	v_mul_f32_e32 v50, v50, v159
	v_mul_f32_e32 v51, v51, v159
	v_mul_f32_e32 v52, v52, v159
	v_mul_f32_e32 v53, v53, v159
	v_cvt_pk_bf16_f32 v50, v50, v51
	v_cvt_pk_bf16_f32 v51, v52, v53
	global_store_dwordx2 v171, v[50:51], s[36:37]
	v_mul_f32_e32 v54, v54, v159
	v_mul_f32_e32 v55, v55, v159
	v_mul_f32_e32 v56, v56, v159
	v_mul_f32_e32 v57, v57, v159
	v_cvt_pk_bf16_f32 v54, v54, v55
	v_cvt_pk_bf16_f32 v55, v56, v57
	global_store_dwordx2 v171, v[54:55], s[36:37] offset:32
	v_mul_f32_e32 v58, v58, v159
	v_mul_f32_e32 v59, v59, v159
	v_mul_f32_e32 v60, v60, v159
	v_mul_f32_e32 v61, v61, v159
	v_cvt_pk_bf16_f32 v58, v58, v59
	v_cvt_pk_bf16_f32 v59, v60, v61
	global_store_dwordx2 v171, v[58:59], s[36:37] offset:64
	v_mul_f32_e32 v62, v62, v159
	v_mul_f32_e32 v63, v63, v159
	v_mul_f32_e32 v64, v64, v159
	v_mul_f32_e32 v65, v65, v159
	v_cvt_pk_bf16_f32 v62, v62, v63
	v_cvt_pk_bf16_f32 v63, v64, v65
	global_store_dwordx2 v171, v[62:63], s[36:37] offset:96
	s_branch .Linpd_done_p0
; DI void st8(u16* dst, const float (&v)[8]) { *(u32x4*)dst = pack8(v); }
; DI void tile_inproj(const Params& p, int l, const Chunk& ck, int tile, int next, PF& pf, char* smem) {
;     ...
;   } else {
;     if (half == 0) {
;       u16* dst = (u16*)(p.ws + OFF_KR) + (size_t)lt * 32;
; #pragma unroll
;       for (int c8 = 0; c8 < 4; ++c8) { cs_ld8(Cs, row, c8 * 8, v);
; #pragma unroll
;         for (int j = 0; j < 8; ++j) v[j] *= rinv;
;         st8(dst + c8 * 8, v); }
;     }
;   }
.Linpd_kr_p0:
	s_cmp_lg_u32 s57, 0
	s_cbranch_scc1 .Linpd_done_p0
	v_lshlrev_b32_e32 v241, 3, v133
	v_mov_b32_e32 v240, v148
	v_lshl_add_u32 v168, v240, 6, v241
	v_add_u32_e32 v240, 16, v148
	v_lshl_add_u32 v169, v240, 6, v241
	v_add_u32_e32 v240, 32, v148
	v_lshl_add_u32 v170, v240, 6, v241
	v_add_u32_e32 v240, 48, v148
	v_lshl_add_u32 v171, v240, 6, v241
	v_mul_f32_e32 v2, v2, v156
	v_mul_f32_e32 v3, v3, v156
	v_mul_f32_e32 v4, v4, v156
	v_mul_f32_e32 v5, v5, v156
	v_cvt_pk_bf16_f32 v2, v2, v3
	v_cvt_pk_bf16_f32 v3, v4, v5
	global_store_dwordx2 v168, v[2:3], s[22:23]
	v_mul_f32_e32 v6, v6, v156
	v_mul_f32_e32 v7, v7, v156
	v_mul_f32_e32 v8, v8, v156
	v_mul_f32_e32 v9, v9, v156
	v_cvt_pk_bf16_f32 v6, v6, v7
	v_cvt_pk_bf16_f32 v7, v8, v9
	global_store_dwordx2 v168, v[6:7], s[22:23] offset:32
	v_mul_f32_e32 v18, v18, v157
	v_mul_f32_e32 v19, v19, v157
	v_mul_f32_e32 v20, v20, v157
	v_mul_f32_e32 v21, v21, v157
	v_cvt_pk_bf16_f32 v18, v18, v19
	v_cvt_pk_bf16_f32 v19, v20, v21
	global_store_dwordx2 v169, v[18:19], s[22:23]
	v_mul_f32_e32 v22, v22, v157
	v_mul_f32_e32 v23, v23, v157
	v_mul_f32_e32 v24, v24, v157
	v_mul_f32_e32 v25, v25, v157
	v_cvt_pk_bf16_f32 v22, v22, v23
	v_cvt_pk_bf16_f32 v23, v24, v25
	global_store_dwordx2 v169, v[22:23], s[22:23] offset:32
	v_mul_f32_e32 v34, v34, v158
	v_mul_f32_e32 v35, v35, v158
	v_mul_f32_e32 v36, v36, v158
	v_mul_f32_e32 v37, v37, v158
	v_cvt_pk_bf16_f32 v34, v34, v35
	v_cvt_pk_bf16_f32 v35, v36, v37
	global_store_dwordx2 v170, v[34:35], s[22:23]
	v_mul_f32_e32 v38, v38, v158
	v_mul_f32_e32 v39, v39, v158
	v_mul_f32_e32 v40, v40, v158
	v_mul_f32_e32 v41, v41, v158
	v_cvt_pk_bf16_f32 v38, v38, v39
	v_cvt_pk_bf16_f32 v39, v40, v41
	global_store_dwordx2 v170, v[38:39], s[22:23] offset:32
	v_mul_f32_e32 v50, v50, v159
	v_mul_f32_e32 v51, v51, v159
	v_mul_f32_e32 v52, v52, v159
	v_mul_f32_e32 v53, v53, v159
	v_cvt_pk_bf16_f32 v50, v50, v51
	v_cvt_pk_bf16_f32 v51, v52, v53
	global_store_dwordx2 v171, v[50:51], s[22:23]
	v_mul_f32_e32 v54, v54, v159
	v_mul_f32_e32 v55, v55, v159
	v_mul_f32_e32 v56, v56, v159
	v_mul_f32_e32 v57, v57, v159
	v_cvt_pk_bf16_f32 v54, v54, v55
	v_cvt_pk_bf16_f32 v55, v56, v57
	global_store_dwordx2 v171, v[54:55], s[22:23] offset:32
.Linpd_done_p0:
	s_add_i32 s12, s30, 1
	s_cmp_eq_u32 s30, 44
	s_cselect_b32 s12, 0x45, s12
	s_cmp_lt_u32 s12, 24
	s_cbranch_scc1 .Linpd_dil_p1
	s_cmp_lt_u32 s12, 41
	s_cbranch_scc1 .Linpd_lat_p1
	s_cmp_lt_u32 s12, 45
	s_cbranch_scc1 .Linpd_mem_p1
	s_branch .Linpd_kr_p1

; DI void tile_inproj(const Params& p, int l, const Chunk& ck, int tile, int next, PF& pf, char* smem) {
;     ...
;     float ssq = 0.f;
; #pragma unroll
;     for (int c8 = 0; c8 < 8; ++c8) { cs_ld8(Cs, row, half * 64 + c8 * 8, v);
; #pragma unroll
;       for (int j = 0; j < 8; ++j) ssq += v[j] * v[j]; }
;     ssq *= rinv * rinv; ssq += __shfl_xor(ssq, 1);
;     const float rn = rsqrtf(ssq * (1.f / 128.f) + EPS) * rinv * scale;
.Linpd_norm_p1:
	global_load_dwordx4 v[224:227], v152, s[34:35] offset:0
	global_load_dwordx4 v[228:231], v152, s[34:35] offset:64
	global_load_dwordx4 v[232:235], v152, s[34:35] offset:128
	global_load_dwordx4 v[236:239], v152, s[34:35] offset:192
	v_mul_f32_e32 v160, v74, v74
	v_fmac_f32_e32 v160, v75, v75
	v_fmac_f32_e32 v160, v76, v76
	v_fmac_f32_e32 v160, v77, v77
	v_fmac_f32_e32 v160, v78, v78
	v_fmac_f32_e32 v160, v79, v79
	v_fmac_f32_e32 v160, v80, v80
	v_fmac_f32_e32 v160, v81, v81
	v_fmac_f32_e32 v160, v82, v82
	v_fmac_f32_e32 v160, v83, v83
	v_fmac_f32_e32 v160, v84, v84
	v_fmac_f32_e32 v160, v85, v85
	v_fmac_f32_e32 v160, v86, v86
	v_fmac_f32_e32 v160, v87, v87
	v_fmac_f32_e32 v160, v88, v88
	v_fmac_f32_e32 v160, v89, v89
	v_mul_f32_e32 v161, v90, v90
	v_fmac_f32_e32 v161, v91, v91
	v_fmac_f32_e32 v161, v92, v92
	v_fmac_f32_e32 v161, v93, v93
	v_fmac_f32_e32 v161, v94, v94
	v_fmac_f32_e32 v161, v95, v95
	v_fmac_f32_e32 v161, v96, v96
	v_fmac_f32_e32 v161, v97, v97
	v_fmac_f32_e32 v161, v98, v98
	v_fmac_f32_e32 v161, v99, v99
	v_fmac_f32_e32 v161, v100, v100
	v_fmac_f32_e32 v161, v101, v101
	v_fmac_f32_e32 v161, v102, v102
	v_fmac_f32_e32 v161, v103, v103
	v_fmac_f32_e32 v161, v104, v104
	v_fmac_f32_e32 v161, v105, v105
	v_mul_f32_e32 v162, v106, v106
	v_fmac_f32_e32 v162, v107, v107
	v_fmac_f32_e32 v162, v108, v108
	v_fmac_f32_e32 v162, v109, v109
	v_fmac_f32_e32 v162, v110, v110
	v_fmac_f32_e32 v162, v111, v111
	v_fmac_f32_e32 v162, v112, v112
	v_fmac_f32_e32 v162, v113, v113
	v_fmac_f32_e32 v162, v114, v114
	v_fmac_f32_e32 v162, v115, v115
	v_fmac_f32_e32 v162, v116, v116
	v_fmac_f32_e32 v162, v117, v117
	v_fmac_f32_e32 v162, v118, v118
	v_fmac_f32_e32 v162, v119, v119
	v_fmac_f32_e32 v162, v120, v120
	v_fmac_f32_e32 v162, v121, v121
	v_mul_f32_e32 v163, v208, v208
	v_fmac_f32_e32 v163, v209, v209
	v_fmac_f32_e32 v163, v210, v210
	v_fmac_f32_e32 v163, v211, v211
	v_fmac_f32_e32 v163, v212, v212
	v_fmac_f32_e32 v163, v213, v213
	v_fmac_f32_e32 v163, v214, v214
	v_fmac_f32_e32 v163, v215, v215
	v_fmac_f32_e32 v163, v216, v216
	v_fmac_f32_e32 v163, v217, v217
	v_fmac_f32_e32 v163, v218, v218
	v_fmac_f32_e32 v163, v219, v219
	v_fmac_f32_e32 v163, v220, v220
	v_fmac_f32_e32 v163, v221, v221
	v_fmac_f32_e32 v163, v222, v222
	v_fmac_f32_e32 v163, v223, v223
	ds_swizzle_b32 v240, v160 offset:0x401f
	ds_swizzle_b32 v241, v161 offset:0x401f
	ds_swizzle_b32 v242, v162 offset:0x401f
	ds_swizzle_b32 v243, v163 offset:0x401f
	s_waitcnt lgkmcnt(0)
	v_add_f32_e32 v160, v160, v240
	v_add_f32_e32 v161, v161, v241
	v_add_f32_e32 v162, v162, v242
	v_add_f32_e32 v163, v163, v243
	v_mov_b32_e32 v240, v160
	v_mov_b32_e32 v241, v161
	v_mov_b32_e32 v242, v162
	v_mov_b32_e32 v243, v163
	s_nop 1
	v_permlane32_swap_b32_e32 v160, v240
	v_permlane32_swap_b32_e32 v161, v241
	v_permlane32_swap_b32_e32 v162, v242
	v_permlane32_swap_b32_e32 v163, v243
	s_nop 1
	v_add_f32_e32 v160, v160, v240
	v_add_f32_e32 v161, v161, v241
	v_add_f32_e32 v162, v162, v242
	v_add_f32_e32 v163, v163, v243
	ds_write_b32 v150, v160 offset:1024
	ds_write_b32 v150, v161 offset:1088
	ds_write_b32 v150, v162 offset:1152
	ds_write_b32 v150, v163 offset:1216
	s_waitcnt lgkmcnt(0)
	s_barrier
	ds_read_b32 v164, v151 offset:1024
	ds_read_b32 v165, v151 offset:1088
	ds_read_b32 v166, v151 offset:1152
	ds_read_b32 v167, v151 offset:1216
	s_waitcnt lgkmcnt(0)
	v_add_f32_e32 v160, v160, v164
	v_mul_f32_e32 v240, v156, v156
	v_add_f32_e32 v161, v161, v165
	v_mul_f32_e32 v241, v157, v157
	v_add_f32_e32 v162, v162, v166
	v_mul_f32_e32 v242, v158, v158
	v_add_f32_e32 v163, v163, v167
	v_mul_f32_e32 v243, v159, v159
	v_mul_f32_e32 v160, v160, v240
	v_fmamk_f32 v160, v160, 0x3c000000, v188
	v_mul_f32_e32 v161, v161, v241
	v_fmamk_f32 v161, v161, 0x3c000000, v188
	v_mul_f32_e32 v162, v162, v242
	v_fmamk_f32 v162, v162, 0x3c000000, v188
	v_mul_f32_e32 v163, v163, v243
	v_fmamk_f32 v163, v163, 0x3c000000, v188
	v_rsq_f32_e32 v160, v160
	v_rsq_f32_e32 v161, v161
	v_rsq_f32_e32 v162, v162
	v_rsq_f32_e32 v163, v163
	s_nop 0
	v_mul_f32_e32 v160, v160, v156
	v_mul_f32_e32 v160, s56, v160
	v_mul_f32_e32 v161, v161, v157
	v_mul_f32_e32 v161, s56, v161
	v_mul_f32_e32 v162, v162, v158
	v_mul_f32_e32 v162, s56, v162
	v_mul_f32_e32 v163, v163, v159
	v_mul_f32_e32 v163, s56, v163
	s_waitcnt vmcnt(0)
; DI void st8(u16* dst, const float (&v)[8]) { *(u32x4*)dst = pack8(v); }
; DI void tile_inproj(const Params& p, int l, const Chunk& ck, int tile, int next, PF& pf, char* smem) {
;     ...
; #pragma unroll
;     for (int c8 = 0; c8 < 8; ++c8) { cs_ld8(Cs, row, half * 64 + c8 * 8, v);
; #pragma unroll
;       for (int j = 0; j < 8; ++j) v[j] = v[j] * rn * gain[half * 64 + c8 * 8 + j];
;       st8(dst + c8 * 8, v); }
	v_mul_f32_e32 v74, v74, v160
	v_mul_f32_e32 v75, v75, v160
	v_mul_f32_e32 v76, v76, v160
	v_mul_f32_e32 v77, v77, v160
	v_mul_f32_e32 v74, v74, v224
	v_mul_f32_e32 v75, v75, v225
	v_mul_f32_e32 v76, v76, v226
	v_mul_f32_e32 v77, v77, v227
	v_cvt_pk_bf16_f32 v74, v74, v75
	v_cvt_pk_bf16_f32 v75, v76, v77
	global_store_dwordx2 v168, v[74:75], s[36:37]
	v_mul_f32_e32 v78, v78, v160
	v_mul_f32_e32 v79, v79, v160
	v_mul_f32_e32 v80, v80, v160
	v_mul_f32_e32 v81, v81, v160
	v_mul_f32_e32 v78, v78, v228
	v_mul_f32_e32 v79, v79, v229
	v_mul_f32_e32 v80, v80, v230
	v_mul_f32_e32 v81, v81, v231
	v_cvt_pk_bf16_f32 v78, v78, v79
	v_cvt_pk_bf16_f32 v79, v80, v81
	global_store_dwordx2 v168, v[78:79], s[36:37] offset:32
	v_mul_f32_e32 v82, v82, v160
	v_mul_f32_e32 v83, v83, v160
	v_mul_f32_e32 v84, v84, v160
	v_mul_f32_e32 v85, v85, v160
	v_mul_f32_e32 v82, v82, v232
	v_mul_f32_e32 v83, v83, v233
	v_mul_f32_e32 v84, v84, v234
	v_mul_f32_e32 v85, v85, v235
	v_cvt_pk_bf16_f32 v82, v82, v83
	v_cvt_pk_bf16_f32 v83, v84, v85
	global_store_dwordx2 v168, v[82:83], s[36:37] offset:64
	v_mul_f32_e32 v86, v86, v160
	v_mul_f32_e32 v87, v87, v160
	v_mul_f32_e32 v88, v88, v160
	v_mul_f32_e32 v89, v89, v160
	v_mul_f32_e32 v86, v86, v236
	v_mul_f32_e32 v87, v87, v237
	v_mul_f32_e32 v88, v88, v238
	v_mul_f32_e32 v89, v89, v239
	v_cvt_pk_bf16_f32 v86, v86, v87
	v_cvt_pk_bf16_f32 v87, v88, v89
	global_store_dwordx2 v168, v[86:87], s[36:37] offset:96
	v_mul_f32_e32 v90, v90, v161
	v_mul_f32_e32 v91, v91, v161
	v_mul_f32_e32 v92, v92, v161
	v_mul_f32_e32 v93, v93, v161
	v_mul_f32_e32 v90, v90, v224
	v_mul_f32_e32 v91, v91, v225
	v_mul_f32_e32 v92, v92, v226
	v_mul_f32_e32 v93, v93, v227
	v_cvt_pk_bf16_f32 v90, v90, v91
	v_cvt_pk_bf16_f32 v91, v92, v93
	global_store_dwordx2 v169, v[90:91], s[36:37]
	v_mul_f32_e32 v94, v94, v161
	v_mul_f32_e32 v95, v95, v161
	v_mul_f32_e32 v96, v96, v161
	v_mul_f32_e32 v97, v97, v161
	v_mul_f32_e32 v94, v94, v228
	v_mul_f32_e32 v95, v95, v229
	v_mul_f32_e32 v96, v96, v230
	v_mul_f32_e32 v97, v97, v231
	v_cvt_pk_bf16_f32 v94, v94, v95
	v_cvt_pk_bf16_f32 v95, v96, v97
	global_store_dwordx2 v169, v[94:95], s[36:37] offset:32
	v_mul_f32_e32 v98, v98, v161
	v_mul_f32_e32 v99, v99, v161
	v_mul_f32_e32 v100, v100, v161
	v_mul_f32_e32 v101, v101, v161
	v_mul_f32_e32 v98, v98, v232
	v_mul_f32_e32 v99, v99, v233
	v_mul_f32_e32 v100, v100, v234
	v_mul_f32_e32 v101, v101, v235
	v_cvt_pk_bf16_f32 v98, v98, v99
	v_cvt_pk_bf16_f32 v99, v100, v101
	global_store_dwordx2 v169, v[98:99], s[36:37] offset:64
	v_mul_f32_e32 v102, v102, v161
	v_mul_f32_e32 v103, v103, v161
	v_mul_f32_e32 v104, v104, v161
	v_mul_f32_e32 v105, v105, v161
	v_mul_f32_e32 v102, v102, v236
	v_mul_f32_e32 v103, v103, v237
	v_mul_f32_e32 v104, v104, v238
	v_mul_f32_e32 v105, v105, v239
	v_cvt_pk_bf16_f32 v102, v102, v103
	v_cvt_pk_bf16_f32 v103, v104, v105
	global_store_dwordx2 v169, v[102:103], s[36:37] offset:96
	v_mul_f32_e32 v106, v106, v162
	v_mul_f32_e32 v107, v107, v162
	v_mul_f32_e32 v108, v108, v162
	v_mul_f32_e32 v109, v109, v162
	v_mul_f32_e32 v106, v106, v224
	v_mul_f32_e32 v107, v107, v225
	v_mul_f32_e32 v108, v108, v226
	v_mul_f32_e32 v109, v109, v227
	v_cvt_pk_bf16_f32 v106, v106, v107
	v_cvt_pk_bf16_f32 v107, v108, v109
	global_store_dwordx2 v170, v[106:107], s[36:37]
	v_mul_f32_e32 v110, v110, v162
	v_mul_f32_e32 v111, v111, v162
	v_mul_f32_e32 v112, v112, v162
	v_mul_f32_e32 v113, v113, v162
	v_mul_f32_e32 v110, v110, v228
	v_mul_f32_e32 v111, v111, v229
	v_mul_f32_e32 v112, v112, v230
	v_mul_f32_e32 v113, v113, v231
	v_cvt_pk_bf16_f32 v110, v110, v111
	v_cvt_pk_bf16_f32 v111, v112, v113
	global_store_dwordx2 v170, v[110:111], s[36:37] offset:32
	v_mul_f32_e32 v114, v114, v162
	v_mul_f32_e32 v115, v115, v162
	v_mul_f32_e32 v116, v116, v162
	v_mul_f32_e32 v117, v117, v162
	v_mul_f32_e32 v114, v114, v232
	v_mul_f32_e32 v115, v115, v233
	v_mul_f32_e32 v116, v116, v234
	v_mul_f32_e32 v117, v117, v235
	v_cvt_pk_bf16_f32 v114, v114, v115
	v_cvt_pk_bf16_f32 v115, v116, v117
	global_store_dwordx2 v170, v[114:115], s[36:37] offset:64
	v_mul_f32_e32 v118, v118, v162
	v_mul_f32_e32 v119, v119, v162
	v_mul_f32_e32 v120, v120, v162
	v_mul_f32_e32 v121, v121, v162
	v_mul_f32_e32 v118, v118, v236
	v_mul_f32_e32 v119, v119, v237
	v_mul_f32_e32 v120, v120, v238
	v_mul_f32_e32 v121, v121, v239
	v_cvt_pk_bf16_f32 v118, v118, v119
	v_cvt_pk_bf16_f32 v119, v120, v121
	global_store_dwordx2 v170, v[118:119], s[36:37] offset:96
	v_mul_f32_e32 v208, v208, v163
	v_mul_f32_e32 v209, v209, v163
	v_mul_f32_e32 v210, v210, v163
	v_mul_f32_e32 v211, v211, v163
	v_mul_f32_e32 v208, v208, v224
	v_mul_f32_e32 v209, v209, v225
	v_mul_f32_e32 v210, v210, v226
	v_mul_f32_e32 v211, v211, v227
	v_cvt_pk_bf16_f32 v208, v208, v209
	v_cvt_pk_bf16_f32 v209, v210, v211
	global_store_dwordx2 v171, v[208:209], s[36:37]
	v_mul_f32_e32 v212, v212, v163
	v_mul_f32_e32 v213, v213, v163
	v_mul_f32_e32 v214, v214, v163
	v_mul_f32_e32 v215, v215, v163
	v_mul_f32_e32 v212, v212, v228
	v_mul_f32_e32 v213, v213, v229
	v_mul_f32_e32 v214, v214, v230
	v_mul_f32_e32 v215, v215, v231
	v_cvt_pk_bf16_f32 v212, v212, v213
	v_cvt_pk_bf16_f32 v213, v214, v215
	global_store_dwordx2 v171, v[212:213], s[36:37] offset:32
	v_mul_f32_e32 v216, v216, v163
	v_mul_f32_e32 v217, v217, v163
	v_mul_f32_e32 v218, v218, v163
	v_mul_f32_e32 v219, v219, v163
	v_mul_f32_e32 v216, v216, v232
	v_mul_f32_e32 v217, v217, v233
	v_mul_f32_e32 v218, v218, v234
	v_mul_f32_e32 v219, v219, v235
	v_cvt_pk_bf16_f32 v216, v216, v217
	v_cvt_pk_bf16_f32 v217, v218, v219
	global_store_dwordx2 v171, v[216:217], s[36:37] offset:64
	v_mul_f32_e32 v220, v220, v163
	v_mul_f32_e32 v221, v221, v163
	v_mul_f32_e32 v222, v222, v163
	v_mul_f32_e32 v223, v223, v163
	v_mul_f32_e32 v220, v220, v236
	v_mul_f32_e32 v221, v221, v237
	v_mul_f32_e32 v222, v222, v238
	v_mul_f32_e32 v223, v223, v239
	v_cvt_pk_bf16_f32 v220, v220, v221
	v_cvt_pk_bf16_f32 v221, v222, v223
	global_store_dwordx2 v171, v[220:221], s[36:37] offset:96
	s_branch .Linpd_done_p1

; DI void st8(u16* dst, const float (&v)[8]) { *(u32x4*)dst = pack8(v); }
; DI void tile_inproj(const Params& p, int l, const Chunk& ck, int tile, int next, PF& pf, char* smem) {
;     ...
;   } else if (ni < 41) {
;     u16* dst = (ni < 39) ? (u16*)(p.ws + OFF_CQ) + (size_t)lt * 384 + (ni - 36) * 128 + half * 64 : (u16*)(p.ws + OFF_CKV) + (size_t)lt * 256 + (ni - 39) * 128 + half * 64;
; #pragma unroll
;     for (int c8 = 0; c8 < 8; ++c8) { cs_ld8(Cs, row, half * 64 + c8 * 8, v);
; #pragma unroll
;       for (int j = 0; j < 8; ++j) v[j] *= rinv;
;       st8(dst + c8 * 8, v); }
.Linpd_plain_p1:
	v_mul_f32_e32 v74, v74, v156
	v_mul_f32_e32 v75, v75, v156
	v_mul_f32_e32 v76, v76, v156
	v_mul_f32_e32 v77, v77, v156
	v_cvt_pk_bf16_f32 v74, v74, v75
	v_cvt_pk_bf16_f32 v75, v76, v77
	global_store_dwordx2 v168, v[74:75], s[36:37]
	v_mul_f32_e32 v78, v78, v156
	v_mul_f32_e32 v79, v79, v156
	v_mul_f32_e32 v80, v80, v156
	v_mul_f32_e32 v81, v81, v156
	v_cvt_pk_bf16_f32 v78, v78, v79
	v_cvt_pk_bf16_f32 v79, v80, v81
	global_store_dwordx2 v168, v[78:79], s[36:37] offset:32
	v_mul_f32_e32 v82, v82, v156
	v_mul_f32_e32 v83, v83, v156
	v_mul_f32_e32 v84, v84, v156
	v_mul_f32_e32 v85, v85, v156
	v_cvt_pk_bf16_f32 v82, v82, v83
	v_cvt_pk_bf16_f32 v83, v84, v85
	global_store_dwordx2 v168, v[82:83], s[36:37] offset:64
	v_mul_f32_e32 v86, v86, v156
	v_mul_f32_e32 v87, v87, v156
	v_mul_f32_e32 v88, v88, v156
	v_mul_f32_e32 v89, v89, v156
	v_cvt_pk_bf16_f32 v86, v86, v87
	v_cvt_pk_bf16_f32 v87, v88, v89
	global_store_dwordx2 v168, v[86:87], s[36:37] offset:96
	v_mul_f32_e32 v90, v90, v157
	v_mul_f32_e32 v91, v91, v157
	v_mul_f32_e32 v92, v92, v157
	v_mul_f32_e32 v93, v93, v157
	v_cvt_pk_bf16_f32 v90, v90, v91
	v_cvt_pk_bf16_f32 v91, v92, v93
	global_store_dwordx2 v169, v[90:91], s[36:37]
	v_mul_f32_e32 v94, v94, v157
	v_mul_f32_e32 v95, v95, v157
	v_mul_f32_e32 v96, v96, v157
	v_mul_f32_e32 v97, v97, v157
	v_cvt_pk_bf16_f32 v94, v94, v95
	v_cvt_pk_bf16_f32 v95, v96, v97
	global_store_dwordx2 v169, v[94:95], s[36:37] offset:32
	v_mul_f32_e32 v98, v98, v157
	v_mul_f32_e32 v99, v99, v157
	v_mul_f32_e32 v100, v100, v157
	v_mul_f32_e32 v101, v101, v157
	v_cvt_pk_bf16_f32 v98, v98, v99
	v_cvt_pk_bf16_f32 v99, v100, v101
	global_store_dwordx2 v169, v[98:99], s[36:37] offset:64
	v_mul_f32_e32 v102, v102, v157
	v_mul_f32_e32 v103, v103, v157
	v_mul_f32_e32 v104, v104, v157
	v_mul_f32_e32 v105, v105, v157
	v_cvt_pk_bf16_f32 v102, v102, v103
	v_cvt_pk_bf16_f32 v103, v104, v105
	global_store_dwordx2 v169, v[102:103], s[36:37] offset:96
	v_mul_f32_e32 v106, v106, v158
	v_mul_f32_e32 v107, v107, v158
	v_mul_f32_e32 v108, v108, v158
	v_mul_f32_e32 v109, v109, v158
	v_cvt_pk_bf16_f32 v106, v106, v107
	v_cvt_pk_bf16_f32 v107, v108, v109
	global_store_dwordx2 v170, v[106:107], s[36:37]
	v_mul_f32_e32 v110, v110, v158
	v_mul_f32_e32 v111, v111, v158
	v_mul_f32_e32 v112, v112, v158
	v_mul_f32_e32 v113, v113, v158
	v_cvt_pk_bf16_f32 v110, v110, v111
	v_cvt_pk_bf16_f32 v111, v112, v113
	global_store_dwordx2 v170, v[110:111], s[36:37] offset:32
	v_mul_f32_e32 v114, v114, v158
	v_mul_f32_e32 v115, v115, v158
	v_mul_f32_e32 v116, v116, v158
	v_mul_f32_e32 v117, v117, v158
	v_cvt_pk_bf16_f32 v114, v114, v115
	v_cvt_pk_bf16_f32 v115, v116, v117
	global_store_dwordx2 v170, v[114:115], s[36:37] offset:64
	v_mul_f32_e32 v118, v118, v158
	v_mul_f32_e32 v119, v119, v158
	v_mul_f32_e32 v120, v120, v158
	v_mul_f32_e32 v121, v121, v158
	v_cvt_pk_bf16_f32 v118, v118, v119
	v_cvt_pk_bf16_f32 v119, v120, v121
	global_store_dwordx2 v170, v[118:119], s[36:37] offset:96
	v_mul_f32_e32 v208, v208, v159
	v_mul_f32_e32 v209, v209, v159
	v_mul_f32_e32 v210, v210, v159
	v_mul_f32_e32 v211, v211, v159
	v_cvt_pk_bf16_f32 v208, v208, v209
	v_cvt_pk_bf16_f32 v209, v210, v211
	global_store_dwordx2 v171, v[208:209], s[36:37]
	v_mul_f32_e32 v212, v212, v159
	v_mul_f32_e32 v213, v213, v159
	v_mul_f32_e32 v214, v214, v159
	v_mul_f32_e32 v215, v215, v159
	v_cvt_pk_bf16_f32 v212, v212, v213
	v_cvt_pk_bf16_f32 v213, v214, v215
	global_store_dwordx2 v171, v[212:213], s[36:37] offset:32
	v_mul_f32_e32 v216, v216, v159
	v_mul_f32_e32 v217, v217, v159
	v_mul_f32_e32 v218, v218, v159
	v_mul_f32_e32 v219, v219, v159
	v_cvt_pk_bf16_f32 v216, v216, v217
	v_cvt_pk_bf16_f32 v217, v218, v219
	global_store_dwordx2 v171, v[216:217], s[36:37] offset:64
	v_mul_f32_e32 v220, v220, v159
	v_mul_f32_e32 v221, v221, v159
	v_mul_f32_e32 v222, v222, v159
	v_mul_f32_e32 v223, v223, v159
	v_cvt_pk_bf16_f32 v220, v220, v221
	v_cvt_pk_bf16_f32 v221, v222, v223
	global_store_dwordx2 v171, v[220:221], s[36:37] offset:96
	s_branch .Linpd_done_p1
; DI void st8(u16* dst, const float (&v)[8]) { *(u32x4*)dst = pack8(v); }
; DI void tile_inproj(const Params& p, int l, const Chunk& ck, int tile, int next, PF& pf, char* smem) {
;     ...
;   } else {
;     if (half == 0) {
;       u16* dst = (u16*)(p.ws + OFF_KR) + (size_t)lt * 32;
; #pragma unroll
;       for (int c8 = 0; c8 < 4; ++c8) { cs_ld8(Cs, row, c8 * 8, v);
; #pragma unroll
;         for (int j = 0; j < 8; ++j) v[j] *= rinv;
;         st8(dst + c8 * 8, v); }
;     }
;   }
.Linpd_kr_p1:
	s_cmp_lg_u32 s57, 0
	s_cbranch_scc1 .Linpd_done_p1
	v_lshlrev_b32_e32 v241, 3, v133
	v_mov_b32_e32 v240, v148
	v_lshl_add_u32 v168, v240, 6, v241
	v_add_u32_e32 v240, 16, v148
	v_lshl_add_u32 v169, v240, 6, v241
	v_add_u32_e32 v240, 32, v148
	v_lshl_add_u32 v170, v240, 6, v241
	v_add_u32_e32 v240, 48, v148
	v_lshl_add_u32 v171, v240, 6, v241
	v_mul_f32_e32 v74, v74, v156
	v_mul_f32_e32 v75, v75, v156
	v_mul_f32_e32 v76, v76, v156
	v_mul_f32_e32 v77, v77, v156
	v_cvt_pk_bf16_f32 v74, v74, v75
	v_cvt_pk_bf16_f32 v75, v76, v77
	global_store_dwordx2 v168, v[74:75], s[22:23]
	v_mul_f32_e32 v78, v78, v156
	v_mul_f32_e32 v79, v79, v156
	v_mul_f32_e32 v80, v80, v156
	v_mul_f32_e32 v81, v81, v156
	v_cvt_pk_bf16_f32 v78, v78, v79
	v_cvt_pk_bf16_f32 v79, v80, v81
	global_store_dwordx2 v168, v[78:79], s[22:23] offset:32
	v_mul_f32_e32 v90, v90, v157
	v_mul_f32_e32 v91, v91, v157
	v_mul_f32_e32 v92, v92, v157
	v_mul_f32_e32 v93, v93, v157
	v_cvt_pk_bf16_f32 v90, v90, v91
	v_cvt_pk_bf16_f32 v91, v92, v93
	global_store_dwordx2 v169, v[90:91], s[22:23]
	v_mul_f32_e32 v94, v94, v157
	v_mul_f32_e32 v95, v95, v157
	v_mul_f32_e32 v96, v96, v157
	v_mul_f32_e32 v97, v97, v157
	v_cvt_pk_bf16_f32 v94, v94, v95
	v_cvt_pk_bf16_f32 v95, v96, v97
	global_store_dwordx2 v169, v[94:95], s[22:23] offset:32
	v_mul_f32_e32 v106, v106, v158
	v_mul_f32_e32 v107, v107, v158
	v_mul_f32_e32 v108, v108, v158
	v_mul_f32_e32 v109, v109, v158
	v_cvt_pk_bf16_f32 v106, v106, v107
	v_cvt_pk_bf16_f32 v107, v108, v109
	global_store_dwordx2 v170, v[106:107], s[22:23]
	v_mul_f32_e32 v110, v110, v158
	v_mul_f32_e32 v111, v111, v158
	v_mul_f32_e32 v112, v112, v158
	v_mul_f32_e32 v113, v113, v158
	v_cvt_pk_bf16_f32 v110, v110, v111
	v_cvt_pk_bf16_f32 v111, v112, v113
	global_store_dwordx2 v170, v[110:111], s[22:23] offset:32
	v_mul_f32_e32 v208, v208, v159
	v_mul_f32_e32 v209, v209, v159
	v_mul_f32_e32 v210, v210, v159
	v_mul_f32_e32 v211, v211, v159
	v_cvt_pk_bf16_f32 v208, v208, v209
	v_cvt_pk_bf16_f32 v209, v210, v211
	global_store_dwordx2 v171, v[208:209], s[22:23]
	v_mul_f32_e32 v212, v212, v159
	v_mul_f32_e32 v213, v213, v159
	v_mul_f32_e32 v214, v214, v159
	v_mul_f32_e32 v215, v215, v159
	v_cvt_pk_bf16_f32 v212, v212, v213
	v_cvt_pk_bf16_f32 v213, v214, v215
	global_store_dwordx2 v171, v[212:213], s[22:23] offset:32
.Linpd_done_p1:
	s_add_i32 s43, s43, s59
	s_add_i32 s75, s75, s95
	s_add_i32 s16, s16, 0x200
	s_cmpk_lt_i32 s16, 0x1700
	s_cbranch_scc1 .LBB1_384
	s_branch .LBB1_409
.Linp_nodirect:
	v_and_b32_e32 v224, 63, v172
	v_lshrrev_b32_e32 v225, 6, v172
	v_lshrrev_b32_e32 v226, 4, v224
	v_lshlrev_b32_e32 v226, 2, v226
	v_lshrrev_b32_e32 v227, 1, v225
	v_lshl_add_u32 v226, v227, 6, v226
	v_mul_u32_u24_e32 v226, 0x84, v226
	v_and_b32_e32 v227, 1, v225
	v_and_b32_e32 v224, 15, v224
	v_lshl_add_u32 v224, v227, 6, v224
	v_add_lshl_u32 v226, v226, v224, 2
	s_cmp_lg_u32 s14, 0
	s_cbranch_scc1 .Linp_w1
	ds_write_b32 v226, v2 offset:0
	ds_write_b32 v226, v3 offset:528
	ds_write_b32 v226, v4 offset:1056
	ds_write_b32 v226, v5 offset:1584
	ds_write_b32 v226, v6 offset:64
	ds_write_b32 v226, v7 offset:592
	ds_write_b32 v226, v8 offset:1120
	ds_write_b32 v226, v9 offset:1648
	ds_write_b32 v226, v10 offset:128
	ds_write_b32 v226, v11 offset:656
	ds_write_b32 v226, v12 offset:1184
	ds_write_b32 v226, v13 offset:1712
	ds_write_b32 v226, v14 offset:192
	ds_write_b32 v226, v15 offset:720
	ds_write_b32 v226, v16 offset:1248
	ds_write_b32 v226, v17 offset:1776
	ds_write_b32 v226, v18 offset:8448
	ds_write_b32 v226, v19 offset:8976
	ds_write_b32 v226, v20 offset:9504
	ds_write_b32 v226, v21 offset:10032
	ds_write_b32 v226, v22 offset:8512
	ds_write_b32 v226, v23 offset:9040
	ds_write_b32 v226, v24 offset:9568
	ds_write_b32 v226, v25 offset:10096
	ds_write_b32 v226, v26 offset:8576
	ds_write_b32 v226, v27 offset:9104
	ds_write_b32 v226, v28 offset:9632
	ds_write_b32 v226, v29 offset:10160
	ds_write_b32 v226, v30 offset:8640
	ds_write_b32 v226, v31 offset:9168
	ds_write_b32 v226, v32 offset:9696
	ds_write_b32 v226, v33 offset:10224
	ds_write_b32 v226, v34 offset:16896
	ds_write_b32 v226, v35 offset:17424
	ds_write_b32 v226, v36 offset:17952
	ds_write_b32 v226, v37 offset:18480
	ds_write_b32 v226, v38 offset:16960
	ds_write_b32 v226, v39 offset:17488
	ds_write_b32 v226, v40 offset:18016
	ds_write_b32 v226, v41 offset:18544
	ds_write_b32 v226, v42 offset:17024
	ds_write_b32 v226, v43 offset:17552
	ds_write_b32 v226, v44 offset:18080
	ds_write_b32 v226, v45 offset:18608
	ds_write_b32 v226, v46 offset:17088
	ds_write_b32 v226, v47 offset:17616
	ds_write_b32 v226, v48 offset:18144
	ds_write_b32 v226, v49 offset:18672
	ds_write_b32 v226, v50 offset:25344
	ds_write_b32 v226, v51 offset:25872
	ds_write_b32 v226, v52 offset:26400
	ds_write_b32 v226, v53 offset:26928
	ds_write_b32 v226, v54 offset:25408
	ds_write_b32 v226, v55 offset:25936
	ds_write_b32 v226, v56 offset:26464
	ds_write_b32 v226, v57 offset:26992
	ds_write_b32 v226, v58 offset:25472
	ds_write_b32 v226, v59 offset:26000
	ds_write_b32 v226, v60 offset:26528
	ds_write_b32 v226, v61 offset:27056
	ds_write_b32 v226, v62 offset:25536
	ds_write_b32 v226, v63 offset:26064
	ds_write_b32 v226, v64 offset:26592
	ds_write_b32 v226, v65 offset:27120
	s_branch .Linp_wd
